# SwiGLU epilogues (phases 7,16): the 8 ss[row] loads issued up front, reloads replaced by register moves, 7 store-draining vmcnt(0) waits per tile removed; on top of batched EpiRes epilogues
# speedup vs baseline: 1.0008x; 1.0005x over previous
; __device__ __forceinline__ unsigned cvt_pk_bf16(float lo, float hi) { unsigned r; asm volatile("v_cvt_pk_bf16_f32 %0, %1, %2" : "=v"(r) : "v"(lo), "v"(hi)); return r; }
; __device__ __forceinline__ float siluf(float v) { return v * __builtin_amdgcn_rcpf(1.0f + __expf(-v)); }
;     __device__ __forceinline__ void operator()(const gacc_t (&acc)[2][2][4][2], const Unit& u, int wr, int wc, int fr, int fq) const {
;         const int row0 = u.pm * 256 + wr * 64 + fr, col0 = u.pn * 128 + wc * 32 + 8 * fq;
;         const int ra = u.pm * 256; const float* shp = shw + (ra < ML ? (ra >> 11) : 8) * (2 * FF) + u.pn * 256 + wc * 32 + 8 * fq;
;         const f32x4 sg0 = *(const f32x4*)shp, sg1 = *(const f32x4*)(shp + 4), su0 = *(const f32x4*)(shp + 128), su1 = *(const f32x4*)(shp + 132);
; #pragma unroll
;         for (int ai = 0; ai < 2; ++ai)
; #pragma unroll
;             for (int m = 0; m < 4; ++m) { bf16_t* rowp = O + (size_t)(row0 + ai * 128 + m * 16) * FF + col0;
;                 const float rs = 1.0f / sqrtf(ss[row0 + ai * 128 + m * 16] * (1.0f / D) + NEPS);
;                 const gacc_t a0 = acc[ai][0][m][0], a1 = acc[ai][0][m][1], b0 = acc[ai][1][m][0], b1 = acc[ai][1][m][1];
;                 const float g0[4] = {a0[0] * rs + sg0.x, a0[1] * rs + sg0.y, a0[2] * rs + sg0.z, a0[3] * rs + sg0.w}, g1[4] = {a1[0] * rs + sg1.x, a1[1] * rs + sg1.y, a1[2] * rs + sg1.z, a1[3] * rs + sg1.w};
;                 const float u0[4] = {b0[0] * rs + su0.x, b0[1] * rs + su0.y, b0[2] * rs + su0.z, b0[3] * rs + su0.w}, u1[4] = {b1[0] * rs + su1.x, b1[1] * rs + su1.y, b1[2] * rs + su1.z, b1[3] * rs + su1.w};
;                 u32x4 w;
;                 w.x = pg8::cvt_pk_bf16(siluf(g0[0]) * u0[0], siluf(g0[1]) * u0[1]); w.y = pg8::cvt_pk_bf16(siluf(g0[2]) * u0[2], siluf(g0[3]) * u0[3]);
;                 w.z = pg8::cvt_pk_bf16(siluf(g1[0]) * u1[0], siluf(g1[1]) * u1[1]); w.w = pg8::cvt_pk_bf16(siluf(g1[2]) * u1[2], siluf(g1[3]) * u1[3]);
;                 *(u32x4*)rowp = w; }
.LBB0_753:
	v_lshl_add_u32 v152, s0, 8, v160
	v_ashrrev_i32_e32 v153, 31, v152
	v_lshl_add_u64 v[158:159], v[152:153], 2, s[8:9]
	s_min_i32 s0, s0, 64
	global_load_dword v153, v[158:159], off
	global_load_dword v190, v[158:159], off offset:64
	global_load_dword v191, v[158:159], off offset:128
	global_load_dword v192, v[158:159], off offset:192
	global_load_dword v193, v[158:159], off offset:512
	global_load_dword v194, v[158:159], off offset:576
	global_load_dword v195, v[158:159], off offset:640
	global_load_dword v196, v[158:159], off offset:704
	s_lshr_b32 s0, s0, 3
	s_mul_i32 s30, s0, 0x2c00
	s_ashr_i32 s31, s30, 31
	s_lshl_b64 s[30:31], s[30:31], 2
	s_add_u32 s0, s54, s30
	s_addc_u32 s23, s55, s31
	s_lshl_b32 s30, s1, 8
	s_ashr_i32 s31, s30, 31
	s_lshl_b64 s[30:31], s[30:31], 2
	s_add_u32 s0, s0, s30
	s_addc_u32 s23, s23, s31
	s_add_u32 s30, s0, s65
	s_addc_u32 s31, s23, 0
	global_load_dwordx4 v[170:173], v166, s[30:31] offset:512
	global_load_dwordx4 v[68:71], v166, s[30:31]
	global_load_dwordx4 v[174:177], v166, s[30:31] offset:528
	global_load_dwordx4 v[64:67], v166, s[30:31] offset:16
	v_mov_b32_e32 v182, v128
	v_mov_b32_e32 v183, v120
	v_mov_b32_e32 v120, v129
	v_mov_b32_e32 v186, v130
	v_lshl_or_b32 v156, s1, 7, v162
	v_mov_b64_e32 v[154:155], s[6:7]
	v_ashrrev_i32_e32 v157, 31, v156
	v_mov_b32_e32 v178, v132
	v_mov_b32_e32 v179, v124
	v_mov_b32_e32 v124, v133
	v_lshlrev_b64 v[132:133], 1, v[156:157]
	v_mov_b32_e32 v187, v122
	v_mov_b32_e32 v122, v131
	v_mov_b32_e32 v180, v134
	v_mov_b32_e32 v181, v126
	v_mov_b32_e32 v126, v135
	s_waitcnt vmcnt(0)
	v_fmamk_f32 v128, v153, 0x3a000000, v167
	v_mul_f32_e32 v129, 0x4f800000, v128
	v_cmp_gt_f32_e32 vcc, s66, v128
	v_mov_b32_e32 v156, v176
	s_nop 0
	v_cndmask_b32_e32 v153, v128, v129, vcc
	v_sqrt_f32_e32 v130, v153
	v_mad_i64_i32 v[128:129], s[0:1], v152, s64, v[154:155]
	v_lshl_add_u64 v[188:189], v[128:129], 0, v[132:133]
	v_add_u32_e32 v128, -1, v130
	v_add_u32_e32 v129, 1, v130
	v_fma_f32 v131, -v128, v130, v153
	v_fma_f32 v134, -v129, v130, v153
	v_cmp_ge_f32_e64 s[0:1], 0, v131
	v_mov_b32_e32 v157, v66
	v_mov_b32_e32 v131, v70
	v_cndmask_b32_e64 v128, v130, v128, s[0:1]
	v_cmp_lt_f32_e64 s[0:1], 0, v134
	v_mov_b32_e32 v130, v172
	v_mov_b32_e32 v70, v173
	v_cndmask_b32_e64 v169, v128, v129, s[0:1]
	v_mul_f32_e32 v66, 0x37800000, v169
	v_cndmask_b32_e32 v66, v169, v66, vcc
	v_cmp_class_f32_e32 vcc, v153, v168
	v_mov_b32_e32 v128, v170
	v_mov_b32_e32 v129, v68
	v_cndmask_b32_e32 v153, v66, v153, vcc
	v_div_scale_f32 v169, s[0:1], v153, v153, 1.0
	v_rcp_f32_e32 v170, v169
	v_mov_b32_e32 v68, v171
	v_div_scale_f32 v171, vcc, 1.0, v153, 1.0
	v_fma_f32 v172, -v169, v170, 1.0
	v_fmac_f32_e32 v170, v172, v170
	v_mul_f32_e32 v172, v171, v170
	v_fma_f32 v173, -v169, v172, v171
	v_fmac_f32_e32 v172, v173, v170
	v_fma_f32 v169, -v169, v172, v171
	v_div_fmas_f32 v169, v169, v170, v172
	v_div_fixup_f32 v170, v169, v153, 1.0
	v_mov_b32_e32 v135, v64
	v_mov_b32_e32 v64, v175
	v_pk_fma_f32 v[124:125], v[124:125], v[170:171], v[68:69] op_sel_hi:[1,0,1]
	v_pk_fma_f32 v[172:173], v[178:179], v[170:171], v[128:129] op_sel_hi:[1,0,1]
	v_pk_fma_f32 v[178:179], v[120:121], v[170:171], v[64:65] op_sel_hi:[1,0,1]
	v_mul_f32_e32 v121, 0xbfb8aa3b, v125
	v_exp_f32_e32 v121, v121
	v_mov_b32_e32 v134, v174
	v_mov_b32_e32 v66, v177
	v_pk_fma_f32 v[126:127], v[126:127], v[170:171], v[70:71] op_sel_hi:[1,0,1]
	v_pk_fma_f32 v[174:175], v[180:181], v[170:171], v[130:131] op_sel_hi:[1,0,1]
	v_pk_fma_f32 v[176:177], v[182:183], v[170:171], v[134:135] op_sel_hi:[1,0,1]
	v_pk_fma_f32 v[180:181], v[186:187], v[170:171], v[156:157] op_sel_hi:[1,0,1]
	v_pk_fma_f32 v[170:171], v[122:123], v[170:171], v[66:67] op_sel_hi:[1,0,1]
	v_mul_f32_e32 v120, 0xbfb8aa3b, v173
	v_mul_f32_e32 v123, 0xbfb8aa3b, v127
	v_mul_f32_e32 v122, 0xbfb8aa3b, v175
	v_exp_f32_e32 v120, v120
	v_exp_f32_e32 v123, v123
	v_mul_f32_e32 v169, 0xbfb8aa3b, v179
	v_exp_f32_e32 v122, v122
	v_add_f32_e32 v121, 1.0, v121
	v_exp_f32_e32 v169, v169
	v_rcp_f32_e32 v121, v121
	v_add_f32_e32 v120, 1.0, v120
	v_add_f32_e32 v123, 1.0, v123
	v_add_f32_e32 v122, 1.0, v122
	v_rcp_f32_e32 v120, v120
	v_rcp_f32_e32 v123, v123
	v_add_f32_e32 v169, 1.0, v169
	v_rcp_f32_e32 v122, v122
	v_mul_f32_e32 v121, v125, v121
	v_mul_f32_e32 v121, v124, v121
	v_rcp_f32_e32 v124, v169
	v_mul_f32_e32 v153, 0xbfb8aa3b, v177
	v_mul_f32_e32 v120, v173, v120
	v_mul_f32_e32 v123, v127, v123
	v_exp_f32_e32 v153, v153
	v_mul_f32_e32 v122, v175, v122
	v_mul_f32_e32 v120, v172, v120
	v_mul_f32_e32 v123, v126, v123
	v_mul_f32_e32 v122, v174, v122
	v_cvt_pk_bf16_f32 v120, v120, v121
	v_cvt_pk_bf16_f32 v121, v122, v123
	v_mul_f32_e32 v123, v179, v124
	v_mul_f32_e32 v124, 0xbfb8aa3b, v181
	v_exp_f32_e32 v124, v124
	v_mul_f32_e32 v125, 0xbfb8aa3b, v171
	v_exp_f32_e32 v125, v125
	v_add_f32_e32 v153, 1.0, v153
	v_rcp_f32_e32 v153, v153
	v_add_f32_e32 v124, 1.0, v124
	v_rcp_f32_e32 v124, v124
	v_add_f32_e32 v125, 1.0, v125
	v_rcp_f32_e32 v125, v125
	v_mul_f32_e32 v122, v177, v153
	v_mul_f32_e32 v122, v176, v122
	v_mul_f32_e32 v123, v178, v123
	v_cvt_pk_bf16_f32 v122, v122, v123
	v_mul_f32_e32 v123, v181, v124
	v_mul_f32_e32 v123, v180, v123
	v_mul_f32_e32 v124, v171, v125
	v_mul_f32_e32 v124, v170, v124
	v_cvt_pk_bf16_f32 v123, v123, v124
	global_store_dwordx4 v[188:189], v[120:123], off
	s_nop 1
	v_or_b32_e32 v120, 16, v152
	v_ashrrev_i32_e32 v121, 31, v120
	v_lshl_add_u64 v[122:123], v[120:121], 2, s[8:9]
	s_nop 1
	v_mov_b32_e32 v121, v190
	v_mov_b32_e32 v123, v112
	v_mov_b32_e32 v112, v117
	v_mov_b32_e32 v117, v114
	v_mov_b32_e32 v114, v119
	v_mov_b32_e32 v119, v104
	v_mov_b32_e32 v104, v109
; __device__ __forceinline__ unsigned cvt_pk_bf16(float lo, float hi) { unsigned r; asm volatile("v_cvt_pk_bf16_f32 %0, %1, %2" : "=v"(r) : "v"(lo), "v"(hi)); return r; }
; __device__ __forceinline__ float siluf(float v) { return v * __builtin_amdgcn_rcpf(1.0f + __expf(-v)); }
;     __device__ __forceinline__ void operator()(const gacc_t (&acc)[2][2][4][2], const Unit& u, int wr, int wc, int fr, int fq) const {
;     ...
;             for (int m = 0; m < 4; ++m) { bf16_t* rowp = O + (size_t)(row0 + ai * 128 + m * 16) * FF + col0;
;                 const float rs = 1.0f / sqrtf(ss[row0 + ai * 128 + m * 16] * (1.0f / D) + NEPS);
;                 const gacc_t a0 = acc[ai][0][m][0], a1 = acc[ai][0][m][1], b0 = acc[ai][1][m][0], b1 = acc[ai][1][m][1];
;                 const float g0[4] = {a0[0] * rs + sg0.x, a0[1] * rs + sg0.y, a0[2] * rs + sg0.z, a0[3] * rs + sg0.w}, g1[4] = {a1[0] * rs + sg1.x, a1[1] * rs + sg1.y, a1[2] * rs + sg1.z, a1[3] * rs + sg1.w};
;                 const float u0[4] = {b0[0] * rs + su0.x, b0[1] * rs + su0.y, b0[2] * rs + su0.z, b0[3] * rs + su0.w}, u1[4] = {b1[0] * rs + su1.x, b1[1] * rs + su1.y, b1[2] * rs + su1.z, b1[3] * rs + su1.w};
;                 u32x4 w;
;                 w.x = pg8::cvt_pk_bf16(siluf(g0[0]) * u0[0], siluf(g0[1]) * u0[1]); w.y = pg8::cvt_pk_bf16(siluf(g0[2]) * u0[2], siluf(g0[3]) * u0[3]);
;                 w.z = pg8::cvt_pk_bf16(siluf(g1[0]) * u1[0], siluf(g1[1]) * u1[1]); w.w = pg8::cvt_pk_bf16(siluf(g1[2]) * u1[2], siluf(g1[3]) * u1[3]);
;                 *(u32x4*)rowp = w; }
	v_mov_b32_e32 v109, v106
	v_mov_b32_e32 v122, v116
	v_mov_b32_e32 v116, v118
	v_mov_b32_e32 v118, v108
	v_mov_b32_e32 v108, v110
	v_fmamk_f32 v106, v121, 0x3a000000, v167
	v_mul_f32_e32 v110, 0x4f800000, v106
	v_cmp_gt_f32_e32 vcc, s66, v106
	s_nop 1
	v_cndmask_b32_e32 v121, v106, v110, vcc
	v_sqrt_f32_e32 v124, v121
	v_mov_b32_e32 v106, v111
	v_mad_i64_i32 v[110:111], s[0:1], v120, s64, v[154:155]
	v_add_u32_e32 v120, -1, v124
	v_add_u32_e32 v125, 1, v124
	v_fma_f32 v126, -v120, v124, v121
	v_fma_f32 v127, -v125, v124, v121
	v_cmp_ge_f32_e64 s[0:1], 0, v126
	v_lshl_add_u64 v[110:111], v[110:111], 0, v[132:133]
	s_nop 0
	v_cndmask_b32_e64 v120, v124, v120, s[0:1]
	v_cmp_lt_f32_e64 s[0:1], 0, v127
	s_nop 1
	v_cndmask_b32_e64 v120, v120, v125, s[0:1]
	v_mul_f32_e32 v124, 0x37800000, v120
	v_cndmask_b32_e32 v120, v120, v124, vcc
	v_cmp_class_f32_e32 vcc, v121, v168
	s_nop 1
	v_cndmask_b32_e32 v120, v120, v121, vcc
	v_div_scale_f32 v121, s[0:1], v120, v120, 1.0
	v_rcp_f32_e32 v124, v121
	v_div_scale_f32 v125, vcc, 1.0, v120, 1.0
	v_fma_f32 v126, -v121, v124, 1.0
	v_fmac_f32_e32 v124, v126, v124
	v_mul_f32_e32 v126, v125, v124
	v_fma_f32 v127, -v121, v126, v125
	v_fmac_f32_e32 v126, v127, v124
	v_fma_f32 v121, -v121, v126, v125
	v_div_fmas_f32 v121, v121, v124, v126
	v_div_fixup_f32 v120, v121, v120, 1.0
	v_pk_fma_f32 v[122:123], v[122:123], v[120:121], v[128:129] op_sel_hi:[1,0,1]
	v_pk_fma_f32 v[112:113], v[112:113], v[120:121], v[68:69] op_sel_hi:[1,0,1]
	v_pk_fma_f32 v[116:117], v[116:117], v[120:121], v[130:131] op_sel_hi:[1,0,1]
	v_pk_fma_f32 v[114:115], v[114:115], v[120:121], v[70:71] op_sel_hi:[1,0,1]
	v_pk_fma_f32 v[118:119], v[118:119], v[120:121], v[134:135] op_sel_hi:[1,0,1]
	v_pk_fma_f32 v[104:105], v[104:105], v[120:121], v[64:65] op_sel_hi:[1,0,1]
	v_pk_fma_f32 v[108:109], v[108:109], v[120:121], v[156:157] op_sel_hi:[1,0,1]
	v_pk_fma_f32 v[120:121], v[106:107], v[120:121], v[66:67] op_sel_hi:[1,0,1]
	v_mul_f32_e32 v106, 0xbfb8aa3b, v123
	v_mul_f32_e32 v107, 0xbfb8aa3b, v113
	v_mul_f32_e32 v124, 0xbfb8aa3b, v117
	v_mul_f32_e32 v125, 0xbfb8aa3b, v115
	v_mul_f32_e32 v127, 0xbfb8aa3b, v105
	v_exp_f32_e32 v106, v106
	v_exp_f32_e32 v107, v107
	v_exp_f32_e32 v124, v124
	v_exp_f32_e32 v125, v125
	v_exp_f32_e32 v127, v127
	v_add_f32_e32 v106, 1.0, v106
	v_add_f32_e32 v107, 1.0, v107
	v_mul_f32_e32 v153, 0xbfb8aa3b, v109
	v_add_f32_e32 v124, 1.0, v124
	v_add_f32_e32 v125, 1.0, v125
	v_add_f32_e32 v127, 1.0, v127
	v_rcp_f32_e32 v106, v106
	v_rcp_f32_e32 v107, v107
	v_mul_f32_e32 v126, 0xbfb8aa3b, v119
	v_mul_f32_e32 v169, 0xbfb8aa3b, v121
	v_exp_f32_e32 v153, v153
	v_rcp_f32_e32 v124, v124
	v_rcp_f32_e32 v125, v125
	v_rcp_f32_e32 v127, v127
	v_exp_f32_e32 v126, v126
	v_exp_f32_e32 v169, v169
	v_mul_f32_e32 v106, v123, v106
	v_mul_f32_e32 v107, v113, v107
	v_add_f32_e32 v153, 1.0, v153
	v_mul_f32_e32 v113, v117, v124
	v_mul_f32_e32 v115, v115, v125
	v_mul_f32_e32 v105, v105, v127
	v_mul_f32_e32 v106, v122, v106
	v_mul_f32_e32 v107, v112, v107
	v_add_f32_e32 v126, 1.0, v126
	v_mul_f32_e32 v112, v116, v113
	v_mul_f32_e32 v113, v114, v115
	v_mul_f32_e32 v115, v104, v105
	v_cvt_pk_bf16_f32 v104, v106, v107
	v_rcp_f32_e32 v107, v153
	v_add_f32_e32 v106, 1.0, v169
	v_rcp_f32_e32 v126, v126
	v_cvt_pk_bf16_f32 v105, v112, v113
	v_rcp_f32_e32 v112, v106
	v_mul_f32_e32 v107, v109, v107
	v_mul_f32_e32 v117, v119, v126
	v_mul_f32_e32 v107, v108, v107
	v_mul_f32_e32 v108, v121, v112
	v_mul_f32_e32 v114, v118, v117
	v_cvt_pk_bf16_f32 v106, v114, v115
	v_mul_f32_e32 v108, v120, v108
	v_cvt_pk_bf16_f32 v107, v107, v108
	global_store_dwordx4 v[110:111], v[104:107], off
	s_nop 1
	v_or_b32_e32 v104, 32, v152
	v_ashrrev_i32_e32 v105, 31, v104
	v_lshl_add_u64 v[106:107], v[104:105], 2, s[8:9]
	s_nop 1
	v_mov_b32_e32 v105, v191
	v_mov_b32_e32 v107, v92
	v_mov_b32_e32 v92, v101
	v_mov_b32_e32 v101, v94
	v_mov_b32_e32 v94, v103
	v_mov_b32_e32 v103, v88
	v_mov_b32_e32 v88, v97
	v_mov_b32_e32 v97, v90
	v_mov_b32_e32 v90, v99
	v_mov_b32_e32 v106, v100
	v_mov_b32_e32 v100, v102
	v_mov_b32_e32 v102, v96
	v_mov_b32_e32 v96, v98
	v_or_b32_e32 v98, 48, v152
	v_fmamk_f32 v99, v105, 0x3a000000, v167
	v_mul_f32_e32 v105, 0x4f800000, v99
	v_cmp_gt_f32_e32 vcc, s66, v99
	s_nop 1
	v_cndmask_b32_e32 v108, v99, v105, vcc
	v_sqrt_f32_e32 v109, v108
	v_mad_i64_i32 v[104:105], s[0:1], v104, s64, v[154:155]
	v_ashrrev_i32_e32 v99, 31, v98
	v_add_u32_e32 v110, -1, v109
	v_add_u32_e32 v111, 1, v109
	v_fma_f32 v112, -v110, v109, v108
	v_fma_f32 v113, -v111, v109, v108
	v_cmp_ge_f32_e64 s[0:1], 0, v112
	v_lshl_add_u64 v[104:105], v[104:105], 0, v[132:133]
	s_nop 0
	v_cndmask_b32_e64 v109, v109, v110, s[0:1]
	v_cmp_lt_f32_e64 s[0:1], 0, v113
	s_nop 1
	v_cndmask_b32_e64 v109, v109, v111, s[0:1]
	v_mul_f32_e32 v110, 0x37800000, v109
	v_cndmask_b32_e32 v109, v109, v110, vcc
	v_cmp_class_f32_e32 vcc, v108, v168
	s_nop 1
	v_cndmask_b32_e32 v108, v109, v108, vcc
	v_div_scale_f32 v109, s[0:1], v108, v108, 1.0
	v_rcp_f32_e32 v110, v109
	v_div_scale_f32 v111, vcc, 1.0, v108, 1.0
	v_fma_f32 v112, -v109, v110, 1.0
	v_fmac_f32_e32 v110, v112, v110
	v_mul_f32_e32 v112, v111, v110
	v_fma_f32 v113, -v109, v112, v111
	v_fmac_f32_e32 v112, v113, v110
	v_fma_f32 v109, -v109, v112, v111
	v_div_fmas_f32 v109, v109, v110, v112
	v_div_fixup_f32 v108, v109, v108, 1.0
	v_pk_fma_f32 v[106:107], v[106:107], v[108:109], v[128:129] op_sel_hi:[1,0,1]
	v_pk_fma_f32 v[92:93], v[92:93], v[108:109], v[68:69] op_sel_hi:[1,0,1]
	v_pk_fma_f32 v[100:101], v[100:101], v[108:109], v[130:131] op_sel_hi:[1,0,1]
	v_pk_fma_f32 v[94:95], v[94:95], v[108:109], v[70:71] op_sel_hi:[1,0,1]
	v_pk_fma_f32 v[88:89], v[88:89], v[108:109], v[64:65] op_sel_hi:[1,0,1]
; __device__ __forceinline__ unsigned cvt_pk_bf16(float lo, float hi) { unsigned r; asm volatile("v_cvt_pk_bf16_f32 %0, %1, %2" : "=v"(r) : "v"(lo), "v"(hi)); return r; }
; __device__ __forceinline__ float siluf(float v) { return v * __builtin_amdgcn_rcpf(1.0f + __expf(-v)); }
;     __device__ __forceinline__ void operator()(const gacc_t (&acc)[2][2][4][2], const Unit& u, int wr, int wc, int fr, int fq) const {
;     ...
;             for (int m = 0; m < 4; ++m) { bf16_t* rowp = O + (size_t)(row0 + ai * 128 + m * 16) * FF + col0;
;                 const float rs = 1.0f / sqrtf(ss[row0 + ai * 128 + m * 16] * (1.0f / D) + NEPS);
;                 const gacc_t a0 = acc[ai][0][m][0], a1 = acc[ai][0][m][1], b0 = acc[ai][1][m][0], b1 = acc[ai][1][m][1];
;                 const float g0[4] = {a0[0] * rs + sg0.x, a0[1] * rs + sg0.y, a0[2] * rs + sg0.z, a0[3] * rs + sg0.w}, g1[4] = {a1[0] * rs + sg1.x, a1[1] * rs + sg1.y, a1[2] * rs + sg1.z, a1[3] * rs + sg1.w};
;                 const float u0[4] = {b0[0] * rs + su0.x, b0[1] * rs + su0.y, b0[2] * rs + su0.z, b0[3] * rs + su0.w}, u1[4] = {b1[0] * rs + su1.x, b1[1] * rs + su1.y, b1[2] * rs + su1.z, b1[3] * rs + su1.w};
;                 u32x4 w;
;                 w.x = pg8::cvt_pk_bf16(siluf(g0[0]) * u0[0], siluf(g0[1]) * u0[1]); w.y = pg8::cvt_pk_bf16(siluf(g0[2]) * u0[2], siluf(g0[3]) * u0[3]);
;                 w.z = pg8::cvt_pk_bf16(siluf(g1[0]) * u1[0], siluf(g1[1]) * u1[1]); w.w = pg8::cvt_pk_bf16(siluf(g1[2]) * u1[2], siluf(g1[3]) * u1[3]);
;                 *(u32x4*)rowp = w; }
	v_pk_fma_f32 v[90:91], v[90:91], v[108:109], v[66:67] op_sel_hi:[1,0,1]
	v_pk_fma_f32 v[102:103], v[102:103], v[108:109], v[134:135] op_sel_hi:[1,0,1]
	v_pk_fma_f32 v[96:97], v[96:97], v[108:109], v[156:157] op_sel_hi:[1,0,1]
	v_mul_f32_e32 v108, 0xbfb8aa3b, v107
	v_mul_f32_e32 v109, 0xbfb8aa3b, v93
	v_mul_f32_e32 v110, 0xbfb8aa3b, v101
	v_mul_f32_e32 v111, 0xbfb8aa3b, v95
	v_mul_f32_e32 v113, 0xbfb8aa3b, v89
	v_mul_f32_e32 v115, 0xbfb8aa3b, v91
	v_mul_f32_e32 v112, 0xbfb8aa3b, v103
	v_mul_f32_e32 v114, 0xbfb8aa3b, v97
	v_exp_f32_e32 v108, v108
	v_exp_f32_e32 v109, v109
	v_exp_f32_e32 v110, v110
	v_exp_f32_e32 v111, v111
	v_exp_f32_e32 v113, v113
	v_exp_f32_e32 v115, v115
	v_exp_f32_e32 v112, v112
	v_exp_f32_e32 v114, v114
	v_add_f32_e32 v108, 1.0, v108
	v_add_f32_e32 v109, 1.0, v109
	v_add_f32_e32 v110, 1.0, v110
	v_add_f32_e32 v111, 1.0, v111
	v_add_f32_e32 v113, 1.0, v113
	v_add_f32_e32 v115, 1.0, v115
	v_add_f32_e32 v112, 1.0, v112
	v_add_f32_e32 v114, 1.0, v114
	v_rcp_f32_e32 v108, v108
	v_rcp_f32_e32 v109, v109
	v_rcp_f32_e32 v110, v110
	v_rcp_f32_e32 v111, v111
	v_rcp_f32_e32 v113, v113
	v_rcp_f32_e32 v115, v115
	v_rcp_f32_e32 v112, v112
	v_rcp_f32_e32 v114, v114
	v_mul_f32_e32 v107, v107, v108
	v_mul_f32_e32 v93, v93, v109
	v_mul_f32_e32 v101, v101, v110
	v_mul_f32_e32 v95, v95, v111
	v_mul_f32_e32 v89, v89, v113
	v_mul_f32_e32 v91, v91, v115
	v_mul_f32_e32 v103, v103, v112
	v_mul_f32_e32 v97, v97, v114
	v_mul_f32_e32 v106, v106, v107
	v_mul_f32_e32 v92, v92, v93
	v_mul_f32_e32 v93, v100, v101
	v_mul_f32_e32 v94, v94, v95
	v_mul_f32_e32 v100, v88, v89
	v_mul_f32_e32 v91, v90, v91
	v_cvt_pk_bf16_f32 v88, v106, v92
	v_cvt_pk_bf16_f32 v89, v93, v94
	v_mul_f32_e32 v95, v102, v103
	v_mul_f32_e32 v96, v96, v97
	v_cvt_pk_bf16_f32 v90, v95, v100
	v_cvt_pk_bf16_f32 v91, v96, v91
	global_store_dwordx4 v[104:105], v[88:91], off
	s_nop 1
	v_lshl_add_u64 v[88:89], v[98:99], 2, s[8:9]
	s_nop 1
	v_mov_b32_e32 v90, v192
	v_mov_b32_e32 v89, v80
	v_mov_b32_e32 v80, v85
	v_mov_b32_e32 v85, v82
	v_mov_b32_e32 v82, v87
	v_mov_b32_e32 v87, v72
	v_mov_b32_e32 v72, v77
	v_mov_b32_e32 v77, v74
	v_mov_b32_e32 v88, v84
	v_mov_b32_e32 v84, v86
	v_mov_b32_e32 v86, v76
	v_mov_b32_e32 v76, v78
	v_fmamk_f32 v74, v90, 0x3a000000, v167
	v_mul_f32_e32 v78, 0x4f800000, v74
	v_cmp_gt_f32_e32 vcc, s66, v74
	s_nop 1
	v_cndmask_b32_e32 v90, v74, v78, vcc
	v_sqrt_f32_e32 v91, v90
	v_mov_b32_e32 v74, v79
	v_mad_i64_i32 v[78:79], s[0:1], v98, s64, v[154:155]
	v_add_u32_e32 v92, -1, v91
	v_add_u32_e32 v93, 1, v91
	v_fma_f32 v94, -v92, v91, v90
	v_fma_f32 v95, -v93, v91, v90
	v_cmp_ge_f32_e64 s[0:1], 0, v94
	v_lshl_add_u64 v[78:79], v[78:79], 0, v[132:133]
	s_nop 0
	v_cndmask_b32_e64 v91, v91, v92, s[0:1]
	v_cmp_lt_f32_e64 s[0:1], 0, v95
	s_nop 1
	v_cndmask_b32_e64 v91, v91, v93, s[0:1]
	v_mul_f32_e32 v92, 0x37800000, v91
	v_cndmask_b32_e32 v91, v91, v92, vcc
	v_cmp_class_f32_e32 vcc, v90, v168
	s_nop 1
	v_cndmask_b32_e32 v90, v91, v90, vcc
	v_div_scale_f32 v91, s[0:1], v90, v90, 1.0
	v_rcp_f32_e32 v92, v91
	v_div_scale_f32 v93, vcc, 1.0, v90, 1.0
	v_fma_f32 v94, -v91, v92, 1.0
	v_fmac_f32_e32 v92, v94, v92
	v_mul_f32_e32 v94, v93, v92
	v_fma_f32 v95, -v91, v94, v93
	v_fmac_f32_e32 v94, v95, v92
	v_fma_f32 v91, -v91, v94, v93
	v_div_fmas_f32 v91, v91, v92, v94
	v_div_fixup_f32 v90, v91, v90, 1.0
	v_pk_fma_f32 v[74:75], v[74:75], v[90:91], v[66:67] op_sel_hi:[1,0,1]
	v_pk_fma_f32 v[88:89], v[88:89], v[90:91], v[128:129] op_sel_hi:[1,0,1]
	v_pk_fma_f32 v[80:81], v[80:81], v[90:91], v[68:69] op_sel_hi:[1,0,1]
	v_pk_fma_f32 v[84:85], v[84:85], v[90:91], v[130:131] op_sel_hi:[1,0,1]
	v_pk_fma_f32 v[82:83], v[82:83], v[90:91], v[70:71] op_sel_hi:[1,0,1]
	v_pk_fma_f32 v[86:87], v[86:87], v[90:91], v[134:135] op_sel_hi:[1,0,1]
	v_pk_fma_f32 v[72:73], v[72:73], v[90:91], v[64:65] op_sel_hi:[1,0,1]
	v_pk_fma_f32 v[76:77], v[76:77], v[90:91], v[156:157] op_sel_hi:[1,0,1]
	v_mul_f32_e32 v97, 0xbfb8aa3b, v75
	v_mul_f32_e32 v90, 0xbfb8aa3b, v89
	v_mul_f32_e32 v91, 0xbfb8aa3b, v81
	v_mul_f32_e32 v92, 0xbfb8aa3b, v85
	v_mul_f32_e32 v93, 0xbfb8aa3b, v83
	v_mul_f32_e32 v94, 0xbfb8aa3b, v87
	v_mul_f32_e32 v95, 0xbfb8aa3b, v73
	v_mul_f32_e32 v96, 0xbfb8aa3b, v77
	v_exp_f32_e32 v97, v97
	v_exp_f32_e32 v90, v90
	v_exp_f32_e32 v91, v91
	v_exp_f32_e32 v92, v92
	v_exp_f32_e32 v93, v93
	v_exp_f32_e32 v94, v94
	v_exp_f32_e32 v95, v95
	v_exp_f32_e32 v96, v96
	v_add_f32_e32 v97, 1.0, v97
	v_add_f32_e32 v90, 1.0, v90
	v_add_f32_e32 v91, 1.0, v91
	v_add_f32_e32 v92, 1.0, v92
	v_add_f32_e32 v93, 1.0, v93
	v_add_f32_e32 v94, 1.0, v94
	v_add_f32_e32 v95, 1.0, v95
	v_add_f32_e32 v96, 1.0, v96
	v_rcp_f32_e32 v97, v97
	v_rcp_f32_e32 v90, v90
	v_rcp_f32_e32 v91, v91
	v_rcp_f32_e32 v92, v92
	v_rcp_f32_e32 v93, v93
	v_rcp_f32_e32 v94, v94
	v_rcp_f32_e32 v95, v95
	v_rcp_f32_e32 v96, v96
	v_mul_f32_e32 v75, v75, v97
	v_mul_f32_e32 v89, v89, v90
	v_mul_f32_e32 v81, v81, v91
	v_mul_f32_e32 v85, v85, v92
	v_mul_f32_e32 v83, v83, v93
	v_mul_f32_e32 v87, v87, v94
	v_mul_f32_e32 v73, v73, v95
	v_mul_f32_e32 v77, v77, v96
	v_mul_f32_e32 v75, v74, v75
	v_mul_f32_e32 v88, v88, v89
	v_mul_f32_e32 v80, v80, v81
	v_mul_f32_e32 v81, v84, v85
	v_mul_f32_e32 v82, v82, v83
	v_mul_f32_e32 v83, v86, v87
	v_mul_f32_e32 v84, v72, v73
	v_mul_f32_e32 v76, v76, v77
	v_cvt_pk_bf16_f32 v72, v88, v80
	v_cvt_pk_bf16_f32 v73, v81, v82
	v_cvt_pk_bf16_f32 v74, v83, v84
	v_cvt_pk_bf16_f32 v75, v76, v75
	global_store_dwordx4 v[78:79], v[72:75], off
	s_nop 1
	v_mov_b32_e32 v74, v193
	s_nop 0
	v_mov_b32_e32 v72, v60
	v_mov_b32_e32 v60, v62
	v_mov_b32_e32 v62, v52
	v_mov_b32_e32 v52, v54
	v_mov_b32_e32 v73, v56
	v_mov_b32_e32 v56, v61
; __device__ __forceinline__ unsigned cvt_pk_bf16(float lo, float hi) { unsigned r; asm volatile("v_cvt_pk_bf16_f32 %0, %1, %2" : "=v"(r) : "v"(lo), "v"(hi)); return r; }
; __device__ __forceinline__ float siluf(float v) { return v * __builtin_amdgcn_rcpf(1.0f + __expf(-v)); }
;     __device__ __forceinline__ void operator()(const gacc_t (&acc)[2][2][4][2], const Unit& u, int wr, int wc, int fr, int fq) const {
;     ...
;             for (int m = 0; m < 4; ++m) { bf16_t* rowp = O + (size_t)(row0 + ai * 128 + m * 16) * FF + col0;
;                 const float rs = 1.0f / sqrtf(ss[row0 + ai * 128 + m * 16] * (1.0f / D) + NEPS);
;                 const gacc_t a0 = acc[ai][0][m][0], a1 = acc[ai][0][m][1], b0 = acc[ai][1][m][0], b1 = acc[ai][1][m][1];
;                 const float g0[4] = {a0[0] * rs + sg0.x, a0[1] * rs + sg0.y, a0[2] * rs + sg0.z, a0[3] * rs + sg0.w}, g1[4] = {a1[0] * rs + sg1.x, a1[1] * rs + sg1.y, a1[2] * rs + sg1.z, a1[3] * rs + sg1.w};
;                 const float u0[4] = {b0[0] * rs + su0.x, b0[1] * rs + su0.y, b0[2] * rs + su0.z, b0[3] * rs + su0.w}, u1[4] = {b1[0] * rs + su1.x, b1[1] * rs + su1.y, b1[2] * rs + su1.z, b1[3] * rs + su1.w};
;                 u32x4 w;
;                 w.x = pg8::cvt_pk_bf16(siluf(g0[0]) * u0[0], siluf(g0[1]) * u0[1]); w.y = pg8::cvt_pk_bf16(siluf(g0[2]) * u0[2], siluf(g0[3]) * u0[3]);
;                 w.z = pg8::cvt_pk_bf16(siluf(g1[0]) * u1[0], siluf(g1[1]) * u1[1]); w.w = pg8::cvt_pk_bf16(siluf(g1[2]) * u1[2], siluf(g1[3]) * u1[3]);
;                 *(u32x4*)rowp = w; }
	v_mov_b32_e32 v61, v58
	v_mov_b32_e32 v58, v63
	v_mov_b32_e32 v63, v48
	v_mov_b32_e32 v48, v53
	v_mov_b32_e32 v53, v50
	v_mov_b32_e32 v50, v55
	v_fmamk_f32 v54, v74, 0x3a000000, v167
	v_mul_f32_e32 v55, 0x4f800000, v54
	v_cmp_gt_f32_e32 vcc, s66, v54
	s_nop 1
	v_cndmask_b32_e32 v74, v54, v55, vcc
	v_sqrt_f32_e32 v75, v74
	v_add_u32_e32 v54, 0x80, v152
	v_mad_i64_i32 v[54:55], s[0:1], v54, s64, v[154:155]
	v_add_u32_e32 v76, -1, v75
	v_add_u32_e32 v77, 1, v75
	v_fma_f32 v78, -v76, v75, v74
	v_fma_f32 v79, -v77, v75, v74
	v_cmp_ge_f32_e64 s[0:1], 0, v78
	v_lshl_add_u64 v[54:55], v[54:55], 0, v[132:133]
	s_nop 0
	v_cndmask_b32_e64 v75, v75, v76, s[0:1]
	v_cmp_lt_f32_e64 s[0:1], 0, v79
	s_nop 1
	v_cndmask_b32_e64 v75, v75, v77, s[0:1]
	v_mul_f32_e32 v76, 0x37800000, v75
	v_cndmask_b32_e32 v75, v75, v76, vcc
	v_cmp_class_f32_e32 vcc, v74, v168
	s_nop 1
	v_cndmask_b32_e32 v74, v75, v74, vcc
	v_div_scale_f32 v75, s[0:1], v74, v74, 1.0
	v_rcp_f32_e32 v76, v75
	v_div_scale_f32 v77, vcc, 1.0, v74, 1.0
	v_fma_f32 v78, -v75, v76, 1.0
	v_fmac_f32_e32 v76, v78, v76
	v_mul_f32_e32 v78, v77, v76
	v_fma_f32 v79, -v75, v78, v77
	v_fmac_f32_e32 v78, v79, v76
	v_fma_f32 v75, -v75, v78, v77
	v_div_fmas_f32 v75, v75, v76, v78
	v_div_fixup_f32 v74, v75, v74, 1.0
	v_pk_fma_f32 v[50:51], v[50:51], v[74:75], v[66:67] op_sel_hi:[1,0,1]
	v_pk_fma_f32 v[72:73], v[72:73], v[74:75], v[128:129] op_sel_hi:[1,0,1]
	v_pk_fma_f32 v[56:57], v[56:57], v[74:75], v[68:69] op_sel_hi:[1,0,1]
	v_pk_fma_f32 v[60:61], v[60:61], v[74:75], v[130:131] op_sel_hi:[1,0,1]
	v_pk_fma_f32 v[58:59], v[58:59], v[74:75], v[70:71] op_sel_hi:[1,0,1]
	v_pk_fma_f32 v[62:63], v[62:63], v[74:75], v[134:135] op_sel_hi:[1,0,1]
	v_pk_fma_f32 v[48:49], v[48:49], v[74:75], v[64:65] op_sel_hi:[1,0,1]
	v_pk_fma_f32 v[52:53], v[52:53], v[74:75], v[156:157] op_sel_hi:[1,0,1]
	v_mul_f32_e32 v81, 0xbfb8aa3b, v51
	v_mul_f32_e32 v74, 0xbfb8aa3b, v73
	v_mul_f32_e32 v75, 0xbfb8aa3b, v57
	v_mul_f32_e32 v76, 0xbfb8aa3b, v61
	v_mul_f32_e32 v77, 0xbfb8aa3b, v59
	v_mul_f32_e32 v78, 0xbfb8aa3b, v63
	v_mul_f32_e32 v79, 0xbfb8aa3b, v49
	v_mul_f32_e32 v80, 0xbfb8aa3b, v53
	v_exp_f32_e32 v81, v81
	v_exp_f32_e32 v74, v74
	v_exp_f32_e32 v75, v75
	v_exp_f32_e32 v76, v76
	v_exp_f32_e32 v77, v77
	v_exp_f32_e32 v78, v78
	v_exp_f32_e32 v79, v79
	v_exp_f32_e32 v80, v80
	v_add_f32_e32 v81, 1.0, v81
	v_add_f32_e32 v74, 1.0, v74
	v_add_f32_e32 v75, 1.0, v75
	v_add_f32_e32 v76, 1.0, v76
	v_add_f32_e32 v77, 1.0, v77
	v_add_f32_e32 v78, 1.0, v78
	v_add_f32_e32 v79, 1.0, v79
	v_add_f32_e32 v80, 1.0, v80
	v_rcp_f32_e32 v81, v81
	v_rcp_f32_e32 v74, v74
	v_rcp_f32_e32 v75, v75
	v_rcp_f32_e32 v76, v76
	v_rcp_f32_e32 v77, v77
	v_rcp_f32_e32 v78, v78
	v_rcp_f32_e32 v79, v79
	v_rcp_f32_e32 v80, v80
	v_mul_f32_e32 v51, v51, v81
	v_mul_f32_e32 v73, v73, v74
	v_mul_f32_e32 v57, v57, v75
	v_mul_f32_e32 v61, v61, v76
	v_mul_f32_e32 v59, v59, v77
	v_mul_f32_e32 v63, v63, v78
	v_mul_f32_e32 v49, v49, v79
	v_mul_f32_e32 v53, v53, v80
	v_mul_f32_e32 v51, v50, v51
	v_mul_f32_e32 v72, v72, v73
	v_mul_f32_e32 v56, v56, v57
	v_mul_f32_e32 v57, v60, v61
	v_mul_f32_e32 v58, v58, v59
	v_mul_f32_e32 v59, v62, v63
	v_mul_f32_e32 v60, v48, v49
	v_mul_f32_e32 v52, v52, v53
	v_cvt_pk_bf16_f32 v48, v72, v56
	v_cvt_pk_bf16_f32 v49, v57, v58
	v_cvt_pk_bf16_f32 v50, v59, v60
	v_cvt_pk_bf16_f32 v51, v52, v51
	global_store_dwordx4 v[54:55], v[48:51], off
	s_nop 1
	v_mov_b32_e32 v50, v194
	s_nop 0
	v_mov_b32_e32 v48, v44
	v_mov_b32_e32 v44, v46
	v_mov_b32_e32 v46, v36
	v_mov_b32_e32 v36, v38
	v_mov_b32_e32 v49, v40
	v_mov_b32_e32 v40, v45
	v_mov_b32_e32 v45, v42
	v_mov_b32_e32 v42, v47
	v_mov_b32_e32 v47, v32
	v_mov_b32_e32 v32, v37
	v_mov_b32_e32 v37, v34
	v_mov_b32_e32 v34, v39
	v_fmamk_f32 v38, v50, 0x3a000000, v167
	v_mul_f32_e32 v39, 0x4f800000, v38
	v_cmp_gt_f32_e32 vcc, s66, v38
	s_nop 1
	v_cndmask_b32_e32 v50, v38, v39, vcc
	v_sqrt_f32_e32 v51, v50
	v_add_u32_e32 v38, 0x90, v152
	v_mad_i64_i32 v[38:39], s[0:1], v38, s64, v[154:155]
	v_add_u32_e32 v52, -1, v51
	v_add_u32_e32 v53, 1, v51
	v_fma_f32 v54, -v52, v51, v50
	v_fma_f32 v55, -v53, v51, v50
	v_cmp_ge_f32_e64 s[0:1], 0, v54
	v_lshl_add_u64 v[38:39], v[38:39], 0, v[132:133]
	s_nop 0
	v_cndmask_b32_e64 v51, v51, v52, s[0:1]
	v_cmp_lt_f32_e64 s[0:1], 0, v55
	s_nop 1
	v_cndmask_b32_e64 v51, v51, v53, s[0:1]
	v_mul_f32_e32 v52, 0x37800000, v51
	v_cndmask_b32_e32 v51, v51, v52, vcc
	v_cmp_class_f32_e32 vcc, v50, v168
	s_nop 1
	v_cndmask_b32_e32 v50, v51, v50, vcc
	v_div_scale_f32 v51, s[0:1], v50, v50, 1.0
	v_rcp_f32_e32 v52, v51
	v_div_scale_f32 v53, vcc, 1.0, v50, 1.0
	v_fma_f32 v54, -v51, v52, 1.0
	v_fmac_f32_e32 v52, v54, v52
	v_mul_f32_e32 v54, v53, v52
	v_fma_f32 v55, -v51, v54, v53
	v_fmac_f32_e32 v54, v55, v52
	v_fma_f32 v51, -v51, v54, v53
	v_div_fmas_f32 v51, v51, v52, v54
	v_div_fixup_f32 v50, v51, v50, 1.0
	v_pk_fma_f32 v[34:35], v[34:35], v[50:51], v[66:67] op_sel_hi:[1,0,1]
	v_pk_fma_f32 v[48:49], v[48:49], v[50:51], v[128:129] op_sel_hi:[1,0,1]
	v_pk_fma_f32 v[40:41], v[40:41], v[50:51], v[68:69] op_sel_hi:[1,0,1]
	v_pk_fma_f32 v[44:45], v[44:45], v[50:51], v[130:131] op_sel_hi:[1,0,1]
	v_pk_fma_f32 v[42:43], v[42:43], v[50:51], v[70:71] op_sel_hi:[1,0,1]
	v_pk_fma_f32 v[46:47], v[46:47], v[50:51], v[134:135] op_sel_hi:[1,0,1]
	v_pk_fma_f32 v[32:33], v[32:33], v[50:51], v[64:65] op_sel_hi:[1,0,1]
	v_pk_fma_f32 v[36:37], v[36:37], v[50:51], v[156:157] op_sel_hi:[1,0,1]
	v_mul_f32_e32 v57, 0xbfb8aa3b, v35
	v_mul_f32_e32 v50, 0xbfb8aa3b, v49
	v_mul_f32_e32 v51, 0xbfb8aa3b, v41
	v_mul_f32_e32 v52, 0xbfb8aa3b, v45
	v_mul_f32_e32 v53, 0xbfb8aa3b, v43
	v_mul_f32_e32 v54, 0xbfb8aa3b, v47
; __device__ __forceinline__ unsigned cvt_pk_bf16(float lo, float hi) { unsigned r; asm volatile("v_cvt_pk_bf16_f32 %0, %1, %2" : "=v"(r) : "v"(lo), "v"(hi)); return r; }
; __device__ __forceinline__ float siluf(float v) { return v * __builtin_amdgcn_rcpf(1.0f + __expf(-v)); }
;     __device__ __forceinline__ void operator()(const gacc_t (&acc)[2][2][4][2], const Unit& u, int wr, int wc, int fr, int fq) const {
;     ...
;             for (int m = 0; m < 4; ++m) { bf16_t* rowp = O + (size_t)(row0 + ai * 128 + m * 16) * FF + col0;
;                 const float rs = 1.0f / sqrtf(ss[row0 + ai * 128 + m * 16] * (1.0f / D) + NEPS);
;                 const gacc_t a0 = acc[ai][0][m][0], a1 = acc[ai][0][m][1], b0 = acc[ai][1][m][0], b1 = acc[ai][1][m][1];
;                 const float g0[4] = {a0[0] * rs + sg0.x, a0[1] * rs + sg0.y, a0[2] * rs + sg0.z, a0[3] * rs + sg0.w}, g1[4] = {a1[0] * rs + sg1.x, a1[1] * rs + sg1.y, a1[2] * rs + sg1.z, a1[3] * rs + sg1.w};
;                 const float u0[4] = {b0[0] * rs + su0.x, b0[1] * rs + su0.y, b0[2] * rs + su0.z, b0[3] * rs + su0.w}, u1[4] = {b1[0] * rs + su1.x, b1[1] * rs + su1.y, b1[2] * rs + su1.z, b1[3] * rs + su1.w};
;                 u32x4 w;
;                 w.x = pg8::cvt_pk_bf16(siluf(g0[0]) * u0[0], siluf(g0[1]) * u0[1]); w.y = pg8::cvt_pk_bf16(siluf(g0[2]) * u0[2], siluf(g0[3]) * u0[3]);
;                 w.z = pg8::cvt_pk_bf16(siluf(g1[0]) * u1[0], siluf(g1[1]) * u1[1]); w.w = pg8::cvt_pk_bf16(siluf(g1[2]) * u1[2], siluf(g1[3]) * u1[3]);
;                 *(u32x4*)rowp = w; }
	v_mul_f32_e32 v55, 0xbfb8aa3b, v33
	v_mul_f32_e32 v56, 0xbfb8aa3b, v37
	v_exp_f32_e32 v57, v57
	v_exp_f32_e32 v50, v50
	v_exp_f32_e32 v51, v51
	v_exp_f32_e32 v52, v52
	v_exp_f32_e32 v53, v53
	v_exp_f32_e32 v54, v54
	v_exp_f32_e32 v55, v55
	v_exp_f32_e32 v56, v56
	v_add_f32_e32 v57, 1.0, v57
	v_add_f32_e32 v50, 1.0, v50
	v_add_f32_e32 v51, 1.0, v51
	v_add_f32_e32 v52, 1.0, v52
	v_add_f32_e32 v53, 1.0, v53
	v_add_f32_e32 v54, 1.0, v54
	v_add_f32_e32 v55, 1.0, v55
	v_add_f32_e32 v56, 1.0, v56
	v_rcp_f32_e32 v57, v57
	v_rcp_f32_e32 v50, v50
	v_rcp_f32_e32 v51, v51
	v_rcp_f32_e32 v52, v52
	v_rcp_f32_e32 v53, v53
	v_rcp_f32_e32 v54, v54
	v_rcp_f32_e32 v55, v55
	v_rcp_f32_e32 v56, v56
	v_mul_f32_e32 v35, v35, v57
	v_mul_f32_e32 v49, v49, v50
	v_mul_f32_e32 v41, v41, v51
	v_mul_f32_e32 v45, v45, v52
	v_mul_f32_e32 v43, v43, v53
	v_mul_f32_e32 v47, v47, v54
	v_mul_f32_e32 v33, v33, v55
	v_mul_f32_e32 v37, v37, v56
	v_mul_f32_e32 v35, v34, v35
	v_mul_f32_e32 v48, v48, v49
	v_mul_f32_e32 v40, v40, v41
	v_mul_f32_e32 v41, v44, v45
	v_mul_f32_e32 v42, v42, v43
	v_mul_f32_e32 v43, v46, v47
	v_mul_f32_e32 v44, v32, v33
	v_mul_f32_e32 v36, v36, v37
	v_cvt_pk_bf16_f32 v32, v48, v40
	v_cvt_pk_bf16_f32 v33, v41, v42
	v_cvt_pk_bf16_f32 v34, v43, v44
	v_cvt_pk_bf16_f32 v35, v36, v35
	global_store_dwordx4 v[38:39], v[32:35], off
	s_nop 1
	v_mov_b32_e32 v34, v195
	s_nop 0
	v_mov_b32_e32 v32, v28
	v_mov_b32_e32 v28, v30
	v_mov_b32_e32 v30, v20
	v_mov_b32_e32 v20, v22
	v_mov_b32_e32 v33, v24
	v_mov_b32_e32 v24, v29
	v_mov_b32_e32 v29, v26
	v_mov_b32_e32 v26, v31
	v_mov_b32_e32 v31, v16
	v_mov_b32_e32 v16, v21
	v_mov_b32_e32 v21, v18
	v_mov_b32_e32 v18, v23
	v_fmamk_f32 v22, v34, 0x3a000000, v167
	v_mul_f32_e32 v23, 0x4f800000, v22
	v_cmp_gt_f32_e32 vcc, s66, v22
	s_nop 1
	v_cndmask_b32_e32 v34, v22, v23, vcc
	v_sqrt_f32_e32 v35, v34
	v_add_u32_e32 v22, 0xa0, v152
	v_mad_i64_i32 v[22:23], s[0:1], v22, s64, v[154:155]
	v_add_u32_e32 v36, -1, v35
	v_add_u32_e32 v37, 1, v35
	v_fma_f32 v38, -v36, v35, v34
	v_fma_f32 v39, -v37, v35, v34
	v_cmp_ge_f32_e64 s[0:1], 0, v38
	v_lshl_add_u64 v[22:23], v[22:23], 0, v[132:133]
	s_nop 0
	v_cndmask_b32_e64 v35, v35, v36, s[0:1]
	v_cmp_lt_f32_e64 s[0:1], 0, v39
	s_nop 1
	v_cndmask_b32_e64 v35, v35, v37, s[0:1]
	v_mul_f32_e32 v36, 0x37800000, v35
	v_cndmask_b32_e32 v35, v35, v36, vcc
	v_cmp_class_f32_e32 vcc, v34, v168
	s_nop 1
	v_cndmask_b32_e32 v34, v35, v34, vcc
	v_div_scale_f32 v35, s[0:1], v34, v34, 1.0
	v_rcp_f32_e32 v36, v35
	v_div_scale_f32 v37, vcc, 1.0, v34, 1.0
	v_fma_f32 v38, -v35, v36, 1.0
	v_fmac_f32_e32 v36, v38, v36
	v_mul_f32_e32 v38, v37, v36
	v_fma_f32 v39, -v35, v38, v37
	v_fmac_f32_e32 v38, v39, v36
	v_fma_f32 v35, -v35, v38, v37
	v_div_fmas_f32 v35, v35, v36, v38
	v_div_fixup_f32 v34, v35, v34, 1.0
	v_pk_fma_f32 v[18:19], v[18:19], v[34:35], v[66:67] op_sel_hi:[1,0,1]
	v_pk_fma_f32 v[32:33], v[32:33], v[34:35], v[128:129] op_sel_hi:[1,0,1]
	v_pk_fma_f32 v[24:25], v[24:25], v[34:35], v[68:69] op_sel_hi:[1,0,1]
	v_pk_fma_f32 v[28:29], v[28:29], v[34:35], v[130:131] op_sel_hi:[1,0,1]
	v_pk_fma_f32 v[26:27], v[26:27], v[34:35], v[70:71] op_sel_hi:[1,0,1]
	v_pk_fma_f32 v[30:31], v[30:31], v[34:35], v[134:135] op_sel_hi:[1,0,1]
	v_pk_fma_f32 v[16:17], v[16:17], v[34:35], v[64:65] op_sel_hi:[1,0,1]
	v_pk_fma_f32 v[20:21], v[20:21], v[34:35], v[156:157] op_sel_hi:[1,0,1]
	v_mul_f32_e32 v41, 0xbfb8aa3b, v19
	v_mul_f32_e32 v34, 0xbfb8aa3b, v33
	v_mul_f32_e32 v35, 0xbfb8aa3b, v25
	v_mul_f32_e32 v36, 0xbfb8aa3b, v29
	v_mul_f32_e32 v37, 0xbfb8aa3b, v27
	v_mul_f32_e32 v38, 0xbfb8aa3b, v31
	v_mul_f32_e32 v39, 0xbfb8aa3b, v17
	v_mul_f32_e32 v40, 0xbfb8aa3b, v21
	v_exp_f32_e32 v41, v41
	v_exp_f32_e32 v34, v34
	v_exp_f32_e32 v35, v35
	v_exp_f32_e32 v36, v36
	v_exp_f32_e32 v37, v37
	v_exp_f32_e32 v38, v38
	v_exp_f32_e32 v39, v39
	v_exp_f32_e32 v40, v40
	v_add_f32_e32 v41, 1.0, v41
	v_add_f32_e32 v34, 1.0, v34
	v_add_f32_e32 v35, 1.0, v35
	v_add_f32_e32 v36, 1.0, v36
	v_add_f32_e32 v37, 1.0, v37
	v_add_f32_e32 v38, 1.0, v38
	v_add_f32_e32 v39, 1.0, v39
	v_add_f32_e32 v40, 1.0, v40
	v_rcp_f32_e32 v41, v41
	v_rcp_f32_e32 v34, v34
	v_rcp_f32_e32 v35, v35
	v_rcp_f32_e32 v36, v36
	v_rcp_f32_e32 v37, v37
	v_rcp_f32_e32 v38, v38
	v_rcp_f32_e32 v39, v39
	v_rcp_f32_e32 v40, v40
	v_mul_f32_e32 v19, v19, v41
; __device__ __forceinline__ unsigned cvt_pk_bf16(float lo, float hi) { unsigned r; asm volatile("v_cvt_pk_bf16_f32 %0, %1, %2" : "=v"(r) : "v"(lo), "v"(hi)); return r; }
; __device__ __forceinline__ float siluf(float v) { return v * __builtin_amdgcn_rcpf(1.0f + __expf(-v)); }
;     __device__ __forceinline__ void operator()(const gacc_t (&acc)[2][2][4][2], const Unit& u, int wr, int wc, int fr, int fq) const {
;     ...
;             for (int m = 0; m < 4; ++m) { bf16_t* rowp = O + (size_t)(row0 + ai * 128 + m * 16) * FF + col0;
;                 const float rs = 1.0f / sqrtf(ss[row0 + ai * 128 + m * 16] * (1.0f / D) + NEPS);
;                 const gacc_t a0 = acc[ai][0][m][0], a1 = acc[ai][0][m][1], b0 = acc[ai][1][m][0], b1 = acc[ai][1][m][1];
;                 const float g0[4] = {a0[0] * rs + sg0.x, a0[1] * rs + sg0.y, a0[2] * rs + sg0.z, a0[3] * rs + sg0.w}, g1[4] = {a1[0] * rs + sg1.x, a1[1] * rs + sg1.y, a1[2] * rs + sg1.z, a1[3] * rs + sg1.w};
;                 const float u0[4] = {b0[0] * rs + su0.x, b0[1] * rs + su0.y, b0[2] * rs + su0.z, b0[3] * rs + su0.w}, u1[4] = {b1[0] * rs + su1.x, b1[1] * rs + su1.y, b1[2] * rs + su1.z, b1[3] * rs + su1.w};
;                 u32x4 w;
;                 w.x = pg8::cvt_pk_bf16(siluf(g0[0]) * u0[0], siluf(g0[1]) * u0[1]); w.y = pg8::cvt_pk_bf16(siluf(g0[2]) * u0[2], siluf(g0[3]) * u0[3]);
;                 w.z = pg8::cvt_pk_bf16(siluf(g1[0]) * u1[0], siluf(g1[1]) * u1[1]); w.w = pg8::cvt_pk_bf16(siluf(g1[2]) * u1[2], siluf(g1[3]) * u1[3]);
;                 *(u32x4*)rowp = w; }
	v_mul_f32_e32 v33, v33, v34
	v_mul_f32_e32 v25, v25, v35
	v_mul_f32_e32 v29, v29, v36
	v_mul_f32_e32 v27, v27, v37
	v_mul_f32_e32 v31, v31, v38
	v_mul_f32_e32 v17, v17, v39
	v_mul_f32_e32 v21, v21, v40
	v_mul_f32_e32 v19, v18, v19
	v_mul_f32_e32 v32, v32, v33
	v_mul_f32_e32 v24, v24, v25
	v_mul_f32_e32 v25, v28, v29
	v_mul_f32_e32 v26, v26, v27
	v_mul_f32_e32 v27, v30, v31
	v_mul_f32_e32 v28, v16, v17
	v_mul_f32_e32 v20, v20, v21
	v_cvt_pk_bf16_f32 v16, v32, v24
	v_cvt_pk_bf16_f32 v17, v25, v26
	v_cvt_pk_bf16_f32 v18, v27, v28
	v_cvt_pk_bf16_f32 v19, v20, v19
	global_store_dwordx4 v[22:23], v[16:19], off
	s_nop 1
	v_mov_b32_e32 v18, v196
	s_nop 0
	v_mov_b32_e32 v17, v4
	v_mov_b32_e32 v4, v13
	v_mov_b32_e32 v13, v6
	v_mov_b32_e32 v6, v15
	v_mov_b32_e32 v15, v0
	v_mov_b32_e32 v0, v9
	v_mov_b32_e32 v9, v2
	v_mov_b32_e32 v2, v11
	v_mov_b32_e32 v16, v12
	v_mov_b32_e32 v12, v14
	v_mov_b32_e32 v14, v8
	v_mov_b32_e32 v8, v10
	v_add_u32_e32 v10, 0xb0, v152
	v_fmamk_f32 v11, v18, 0x3a000000, v167
	v_mul_f32_e32 v18, 0x4f800000, v11
	v_cmp_gt_f32_e32 vcc, s66, v11
	s_nop 1
	v_cndmask_b32_e32 v18, v11, v18, vcc
	v_sqrt_f32_e32 v19, v18
	v_mad_i64_i32 v[10:11], s[0:1], v10, s64, v[154:155]
	v_lshl_add_u64 v[10:11], v[10:11], 0, v[132:133]
	v_add_u32_e32 v20, -1, v19
	v_add_u32_e32 v21, 1, v19
	v_fma_f32 v22, -v20, v19, v18
	v_fma_f32 v23, -v21, v19, v18
	v_cmp_ge_f32_e64 s[0:1], 0, v22
	s_nop 1
	v_cndmask_b32_e64 v19, v19, v20, s[0:1]
	v_cmp_lt_f32_e64 s[0:1], 0, v23
	s_nop 1
	v_cndmask_b32_e64 v19, v19, v21, s[0:1]
	v_mul_f32_e32 v20, 0x37800000, v19
	v_cndmask_b32_e32 v19, v19, v20, vcc
	v_cmp_class_f32_e32 vcc, v18, v168
	s_nop 1
	v_cndmask_b32_e32 v18, v19, v18, vcc
	v_div_scale_f32 v19, s[0:1], v18, v18, 1.0
	v_rcp_f32_e32 v20, v19
	v_div_scale_f32 v21, vcc, 1.0, v18, 1.0
	s_mov_b64 s[0:1], -1
	v_fma_f32 v22, -v19, v20, 1.0
	v_fmac_f32_e32 v20, v22, v20
	v_mul_f32_e32 v22, v21, v20
	v_fma_f32 v23, -v19, v22, v21
	v_fmac_f32_e32 v22, v23, v20
	v_fma_f32 v19, -v19, v22, v21
	v_div_fmas_f32 v19, v19, v20, v22
	v_div_fixup_f32 v18, v19, v18, 1.0
	v_pk_fma_f32 v[2:3], v[2:3], v[18:19], v[66:67] op_sel_hi:[1,0,1]
	v_pk_fma_f32 v[16:17], v[16:17], v[18:19], v[128:129] op_sel_hi:[1,0,1]
	v_pk_fma_f32 v[4:5], v[4:5], v[18:19], v[68:69] op_sel_hi:[1,0,1]
	v_pk_fma_f32 v[12:13], v[12:13], v[18:19], v[130:131] op_sel_hi:[1,0,1]
	v_pk_fma_f32 v[6:7], v[6:7], v[18:19], v[70:71] op_sel_hi:[1,0,1]
	v_pk_fma_f32 v[14:15], v[14:15], v[18:19], v[134:135] op_sel_hi:[1,0,1]
	v_pk_fma_f32 v[0:1], v[0:1], v[18:19], v[64:65] op_sel_hi:[1,0,1]
	v_pk_fma_f32 v[8:9], v[8:9], v[18:19], v[156:157] op_sel_hi:[1,0,1]
	v_mul_f32_e32 v25, 0xbfb8aa3b, v3
	v_mul_f32_e32 v18, 0xbfb8aa3b, v17
	v_mul_f32_e32 v19, 0xbfb8aa3b, v5
	v_mul_f32_e32 v20, 0xbfb8aa3b, v13
	v_mul_f32_e32 v21, 0xbfb8aa3b, v7
	v_mul_f32_e32 v22, 0xbfb8aa3b, v15
	v_mul_f32_e32 v23, 0xbfb8aa3b, v1
	v_mul_f32_e32 v24, 0xbfb8aa3b, v9
	v_exp_f32_e32 v25, v25
	v_exp_f32_e32 v18, v18
	v_exp_f32_e32 v19, v19
	v_exp_f32_e32 v20, v20
	v_exp_f32_e32 v21, v21
	v_exp_f32_e32 v22, v22
	v_exp_f32_e32 v23, v23
	v_exp_f32_e32 v24, v24
	v_add_f32_e32 v25, 1.0, v25
	v_add_f32_e32 v18, 1.0, v18
	v_add_f32_e32 v19, 1.0, v19
	v_add_f32_e32 v20, 1.0, v20
	v_add_f32_e32 v21, 1.0, v21
	v_add_f32_e32 v22, 1.0, v22
	v_add_f32_e32 v23, 1.0, v23
	v_add_f32_e32 v24, 1.0, v24
	v_rcp_f32_e32 v25, v25
	v_rcp_f32_e32 v18, v18
	v_rcp_f32_e32 v19, v19
	v_rcp_f32_e32 v20, v20
	v_rcp_f32_e32 v21, v21
	v_rcp_f32_e32 v22, v22
	v_rcp_f32_e32 v23, v23
	v_rcp_f32_e32 v24, v24
	v_mul_f32_e32 v3, v3, v25
	s_andn2_b64 vcc, exec, s[2:3]
	v_mul_f32_e32 v17, v17, v18
	v_mul_f32_e32 v5, v5, v19
	v_mul_f32_e32 v13, v13, v20
	v_mul_f32_e32 v7, v7, v21
	v_mul_f32_e32 v15, v15, v22
	v_mul_f32_e32 v1, v1, v23
	v_mul_f32_e32 v9, v9, v24
	v_mul_f32_e32 v3, v2, v3
	v_mul_f32_e32 v16, v16, v17
	v_mul_f32_e32 v4, v4, v5
	v_mul_f32_e32 v5, v12, v13
	v_mul_f32_e32 v6, v6, v7
	v_mul_f32_e32 v7, v14, v15
	v_mul_f32_e32 v12, v0, v1
	v_mul_f32_e32 v8, v8, v9
	v_cvt_pk_bf16_f32 v0, v16, v4
	v_cvt_pk_bf16_f32 v1, v5, v6
	v_cvt_pk_bf16_f32 v2, v7, v12
	v_cvt_pk_bf16_f32 v3, v8, v3
	global_store_dwordx4 v[10:11], v[0:3], off
	s_cbranch_vccnz .LBB0_746
	s_andn2_b64 vcc, exec, s[4:5]
	s_cbranch_vccnz .LBB0_745
	s_barrier
	s_branch .LBB0_745

; __device__ __forceinline__ unsigned cvt_pk_bf16(float lo, float hi) { unsigned r; asm volatile("v_cvt_pk_bf16_f32 %0, %1, %2" : "=v"(r) : "v"(lo), "v"(hi)); return r; }
;     __device__ __forceinline__ void operator()(const gacc_t (&acc)[2][2][4][2], const Unit& u, int wr, int wc, int fr, int fq) const {
;     ...
;             for (int m = 0; m < 4; ++m) { const int row = u.pm * 256 + ai * 128 + wr * 64 + m * 16 + fr;
;                 const float* bp = row < ML ? baseL + (size_t)row * D : baseC + (size_t)(row - ML) * D;
;                 const int mb = row < ML ? (row >> 11) : 8; const float* gp = mod + mb * MODW + chunk * D; float* op = out + (size_t)row * D;
;                 float sq = 0.f;
; #pragma unroll
;                 for (int bj = 0; bj < 2; ++bj)
; #pragma unroll
;                     for (int n = 0; n < 2; ++n) { const int col = u.pn * 256 + bj * 128 + wc * 32 + n * 16 + 4 * fq;
;                         const f32x4 b = *(const f32x4*)(bp + col), g = *(const f32x4*)(gp + col); const gacc_t a = acc[ai][bj][m][n];
;                         f32x4 o; o.x = b.x + g.x * a[0]; o.y = b.y + g.y * a[1]; o.z = b.z + g.z * a[2]; o.w = b.w + g.w * a[3];
;                         *(f32x4*)(op + col) = o;
;                         if (hu) { const f32x4 gg = *(const f32x4*)(gn + col), sc = *(const f32x4*)(scl + mb * MODW + col);
;                             sq += (o.x * o.x + o.y * o.y) + (o.z * o.z + o.w * o.w);
;                             u32x2 w; w.x = pg8::cvt_pk_bf16(o.x * gg.x * (1.f + sc.x), o.y * gg.y * (1.f + sc.y)); w.y = pg8::cvt_pk_bf16(o.z * gg.z * (1.f + sc.z), o.w * gg.w * (1.f + sc.w));
;                             *(u32x2*)(hu + (size_t)row * D + col) = w; } }
.LBB0_831:
	s_lshl_b32 s48, s75, 8
	s_add_i32 s48, s48, s60
	s_lshr_b32 s45, s48, 11
	s_mul_i32 s45, s45, 0xc000
	s_cmpk_gt_i32 s48, 0x3fff
	s_cselect_b32 s45, 0x60000, s45
	s_cselect_b32 s46, s22, s10
	s_cselect_b32 s47, s23, s11
	v_lshl_or_b32 v132, s74, 8, v154
	v_lshlrev_b32_e32 v132, 2, v132
	v_add_u32_e32 v222, s45, v132
	v_add_u32_e32 v223, s36, v222
	v_add_u32_e32 v220, s48, v152
	v_lshl_add_u32 v219, v220, 13, v132
	s_cselect_b32 s45, 0x8000000, 0
	s_sub_u32 s46, s46, s45
	s_subb_u32 s47, s47, 0
	v_mov_b32_e32 v218, v219
	global_load_dwordx4 v[142:145], v222, s[26:27] offset:0
	global_load_dwordx4 v[146:149], v222, s[26:27] offset:64
	global_load_dwordx4 v[176:179], v222, s[26:27] offset:512
	global_load_dwordx4 v[180:183], v222, s[26:27] offset:576
	global_load_dwordx4 v[186:189], v132, s[24:25] offset:0
	global_load_dwordx4 v[190:193], v132, s[24:25] offset:64
	global_load_dwordx4 v[194:197], v132, s[24:25] offset:512
	global_load_dwordx4 v[198:201], v132, s[24:25] offset:576
	global_load_dwordx4 v[160:163], v223, s[8:9] offset:0
	global_load_dwordx4 v[164:167], v223, s[8:9] offset:64
	global_load_dwordx4 v[168:171], v223, s[8:9] offset:512
	global_load_dwordx4 v[172:175], v223, s[8:9] offset:576
	global_load_dwordx4 v[202:205], v218, s[46:47] offset:0
	global_load_dwordx4 v[206:209], v218, s[46:47] offset:64
	global_load_dwordx4 v[210:213], v218, s[46:47] offset:512
	global_load_dwordx4 v[214:217], v218, s[46:47] offset:576
	v_add_u32_e32 v218, 0x20000, v218
	s_waitcnt vmcnt(8)
	v_add_f32_e32 v142, 1.0, v142
	v_add_f32_e32 v143, 1.0, v143
	v_add_f32_e32 v144, 1.0, v144
	v_add_f32_e32 v145, 1.0, v145
	v_add_f32_e32 v146, 1.0, v146
	v_add_f32_e32 v147, 1.0, v147
	v_add_f32_e32 v148, 1.0, v148
	v_add_f32_e32 v149, 1.0, v149
	v_add_f32_e32 v176, 1.0, v176
	v_add_f32_e32 v177, 1.0, v177
	v_add_f32_e32 v178, 1.0, v178
	v_add_f32_e32 v179, 1.0, v179
	v_add_f32_e32 v180, 1.0, v180
	v_add_f32_e32 v181, 1.0, v181
	v_add_f32_e32 v182, 1.0, v182
	v_add_f32_e32 v183, 1.0, v183
	v_mul_f32_e32 v186, v186, v142
	v_mul_f32_e32 v187, v187, v143
	v_mul_f32_e32 v188, v188, v144
	v_mul_f32_e32 v189, v189, v145
	v_mul_f32_e32 v190, v190, v146
	v_mul_f32_e32 v191, v191, v147
	v_mul_f32_e32 v192, v192, v148
	v_mul_f32_e32 v193, v193, v149
	v_mul_f32_e32 v194, v194, v176
	v_mul_f32_e32 v195, v195, v177
	v_mul_f32_e32 v196, v196, v178
	v_mul_f32_e32 v197, v197, v179
	v_mul_f32_e32 v198, v198, v180
	v_mul_f32_e32 v199, v199, v181
	v_mul_f32_e32 v200, v200, v182
	v_mul_f32_e32 v201, v201, v183
	global_load_dwordx4 v[142:145], v218, s[46:47] offset:0
	global_load_dwordx4 v[146:149], v218, s[46:47] offset:64
	global_load_dwordx4 v[176:179], v218, s[46:47] offset:512
	global_load_dwordx4 v[180:183], v218, s[46:47] offset:576
	v_add_u32_e32 v218, 0x20000, v218
	s_waitcnt vmcnt(4)
	v_pk_fma_f32 v[126:127], v[126:127], v[162:163], v[204:205]
	v_pk_fma_f32 v[124:125], v[124:125], v[160:161], v[202:203]
	global_store_dwordx4 v219, v[124:127], s[10:11] offset:0
	v_pk_fma_f32 v[122:123], v[122:123], v[166:167], v[208:209]
	v_pk_fma_f32 v[120:121], v[120:121], v[164:165], v[206:207]
	global_store_dwordx4 v219, v[120:123], s[10:11] offset:64
	v_pk_fma_f32 v[118:119], v[118:119], v[170:171], v[212:213]
	v_pk_fma_f32 v[116:117], v[116:117], v[168:169], v[210:211]
	global_store_dwordx4 v219, v[116:119], s[10:11] offset:512
	v_pk_fma_f32 v[114:115], v[114:115], v[174:175], v[216:217]
	v_pk_fma_f32 v[112:113], v[112:113], v[172:173], v[214:215]
	global_store_dwordx4 v219, v[112:115], s[10:11] offset:576
	v_lshrrev_b32_e32 v220, 1, v219
	v_mul_f32_e32 v202, v124, v186
	v_mul_f32_e32 v203, v125, v187
	v_mul_f32_e32 v204, v126, v188
	v_mul_f32_e32 v205, v127, v189
	v_mul_f32_e32 v221, v124, v124
	v_fmac_f32_e32 v221, v125, v125
	v_fmac_f32_e32 v221, v126, v126
	v_fmac_f32_e32 v221, v127, v127
	v_cvt_pk_bf16_f32 v202, v202, v203
	v_cvt_pk_bf16_f32 v203, v204, v205
	global_store_dwordx2 v220, v[202:203], s[14:15] offset:0
	v_mul_f32_e32 v206, v120, v190
	v_mul_f32_e32 v207, v121, v191
	v_mul_f32_e32 v208, v122, v192
	v_mul_f32_e32 v209, v123, v193
	v_fmac_f32_e32 v221, v120, v120
	v_fmac_f32_e32 v221, v121, v121
	v_fmac_f32_e32 v221, v122, v122
	v_fmac_f32_e32 v221, v123, v123
	v_cvt_pk_bf16_f32 v206, v206, v207
	v_cvt_pk_bf16_f32 v207, v208, v209
	global_store_dwordx2 v220, v[206:207], s[14:15] offset:32
	v_mul_f32_e32 v210, v116, v194
	v_mul_f32_e32 v211, v117, v195
	v_mul_f32_e32 v212, v118, v196
	v_mul_f32_e32 v213, v119, v197
	v_fmac_f32_e32 v221, v116, v116
	v_fmac_f32_e32 v221, v117, v117
	v_fmac_f32_e32 v221, v118, v118
	v_fmac_f32_e32 v221, v119, v119
	v_cvt_pk_bf16_f32 v210, v210, v211
	v_cvt_pk_bf16_f32 v211, v212, v213
	global_store_dwordx2 v220, v[210:211], s[14:15] offset:256
	v_mul_f32_e32 v214, v112, v198
	v_mul_f32_e32 v215, v113, v199
	v_mul_f32_e32 v216, v114, v200
	v_mul_f32_e32 v217, v115, v201
	v_fmac_f32_e32 v221, v112, v112
	v_fmac_f32_e32 v221, v113, v113
	v_fmac_f32_e32 v221, v114, v114
	v_fmac_f32_e32 v221, v115, v115
	v_cvt_pk_bf16_f32 v214, v214, v215
	v_cvt_pk_bf16_f32 v215, v216, v217
	global_store_dwordx2 v220, v[214:215], s[14:15] offset:288
	v_mov_b32_e32 v124, v221
	global_load_dwordx4 v[202:205], v218, s[46:47] offset:0
	global_load_dwordx4 v[206:209], v218, s[46:47] offset:64
	global_load_dwordx4 v[210:213], v218, s[46:47] offset:512
	global_load_dwordx4 v[214:217], v218, s[46:47] offset:576
	v_add_u32_e32 v218, 0x20000, v218
	v_add_u32_e32 v219, 0x20000, v219
	s_waitcnt vmcnt(12)
; __device__ __forceinline__ unsigned cvt_pk_bf16(float lo, float hi) { unsigned r; asm volatile("v_cvt_pk_bf16_f32 %0, %1, %2" : "=v"(r) : "v"(lo), "v"(hi)); return r; }
;     __device__ __forceinline__ void operator()(const gacc_t (&acc)[2][2][4][2], const Unit& u, int wr, int wc, int fr, int fq) const {
;     ...
;                     for (int n = 0; n < 2; ++n) { const int col = u.pn * 256 + bj * 128 + wc * 32 + n * 16 + 4 * fq;
;                         const f32x4 b = *(const f32x4*)(bp + col), g = *(const f32x4*)(gp + col); const gacc_t a = acc[ai][bj][m][n];
;                         f32x4 o; o.x = b.x + g.x * a[0]; o.y = b.y + g.y * a[1]; o.z = b.z + g.z * a[2]; o.w = b.w + g.w * a[3];
;                         *(f32x4*)(op + col) = o;
;                         if (hu) { const f32x4 gg = *(const f32x4*)(gn + col), sc = *(const f32x4*)(scl + mb * MODW + col);
;                             sq += (o.x * o.x + o.y * o.y) + (o.z * o.z + o.w * o.w);
;                             u32x2 w; w.x = pg8::cvt_pk_bf16(o.x * gg.x * (1.f + sc.x), o.y * gg.y * (1.f + sc.y)); w.y = pg8::cvt_pk_bf16(o.z * gg.z * (1.f + sc.z), o.w * gg.w * (1.f + sc.w));
;                             *(u32x2*)(hu + (size_t)row * D + col) = w; } }
	v_pk_fma_f32 v[110:111], v[110:111], v[162:163], v[144:145]
	v_pk_fma_f32 v[108:109], v[108:109], v[160:161], v[142:143]
	global_store_dwordx4 v219, v[108:111], s[10:11] offset:0
	v_pk_fma_f32 v[106:107], v[106:107], v[166:167], v[148:149]
	v_pk_fma_f32 v[104:105], v[104:105], v[164:165], v[146:147]
	global_store_dwordx4 v219, v[104:107], s[10:11] offset:64
	v_pk_fma_f32 v[102:103], v[102:103], v[170:171], v[178:179]
	v_pk_fma_f32 v[100:101], v[100:101], v[168:169], v[176:177]
	global_store_dwordx4 v219, v[100:103], s[10:11] offset:512
	v_pk_fma_f32 v[98:99], v[98:99], v[174:175], v[182:183]
	v_pk_fma_f32 v[96:97], v[96:97], v[172:173], v[180:181]
	global_store_dwordx4 v219, v[96:99], s[10:11] offset:576
	v_lshrrev_b32_e32 v220, 1, v219
	v_mul_f32_e32 v142, v108, v186
	v_mul_f32_e32 v143, v109, v187
	v_mul_f32_e32 v144, v110, v188
	v_mul_f32_e32 v145, v111, v189
	v_mul_f32_e32 v221, v108, v108
	v_fmac_f32_e32 v221, v109, v109
	v_fmac_f32_e32 v221, v110, v110
	v_fmac_f32_e32 v221, v111, v111
	v_cvt_pk_bf16_f32 v142, v142, v143
	v_cvt_pk_bf16_f32 v143, v144, v145
	global_store_dwordx2 v220, v[142:143], s[14:15] offset:0
	v_mul_f32_e32 v146, v104, v190
	v_mul_f32_e32 v147, v105, v191
	v_mul_f32_e32 v148, v106, v192
	v_mul_f32_e32 v149, v107, v193
	v_fmac_f32_e32 v221, v104, v104
	v_fmac_f32_e32 v221, v105, v105
	v_fmac_f32_e32 v221, v106, v106
	v_fmac_f32_e32 v221, v107, v107
	v_cvt_pk_bf16_f32 v146, v146, v147
	v_cvt_pk_bf16_f32 v147, v148, v149
	global_store_dwordx2 v220, v[146:147], s[14:15] offset:32
	v_mul_f32_e32 v176, v100, v194
	v_mul_f32_e32 v177, v101, v195
	v_mul_f32_e32 v178, v102, v196
	v_mul_f32_e32 v179, v103, v197
	v_fmac_f32_e32 v221, v100, v100
	v_fmac_f32_e32 v221, v101, v101
	v_fmac_f32_e32 v221, v102, v102
	v_fmac_f32_e32 v221, v103, v103
	v_cvt_pk_bf16_f32 v176, v176, v177
	v_cvt_pk_bf16_f32 v177, v178, v179
	global_store_dwordx2 v220, v[176:177], s[14:15] offset:256
	v_mul_f32_e32 v180, v96, v198
	v_mul_f32_e32 v181, v97, v199
	v_mul_f32_e32 v182, v98, v200
	v_mul_f32_e32 v183, v99, v201
	v_fmac_f32_e32 v221, v96, v96
	v_fmac_f32_e32 v221, v97, v97
	v_fmac_f32_e32 v221, v98, v98
	v_fmac_f32_e32 v221, v99, v99
	v_cvt_pk_bf16_f32 v180, v180, v181
	v_cvt_pk_bf16_f32 v181, v182, v183
	global_store_dwordx2 v220, v[180:181], s[14:15] offset:288
	v_mov_b32_e32 v108, v221
	global_load_dwordx4 v[142:145], v218, s[46:47] offset:0
	global_load_dwordx4 v[146:149], v218, s[46:47] offset:64
	global_load_dwordx4 v[176:179], v218, s[46:47] offset:512
	global_load_dwordx4 v[180:183], v218, s[46:47] offset:576
	v_add_u32_e32 v218, 0xa0000, v218
	v_add_u32_e32 v219, 0x20000, v219
	s_waitcnt vmcnt(12)
	v_pk_fma_f32 v[94:95], v[94:95], v[162:163], v[204:205]
	v_pk_fma_f32 v[92:93], v[92:93], v[160:161], v[202:203]
	global_store_dwordx4 v219, v[92:95], s[10:11] offset:0
	v_pk_fma_f32 v[90:91], v[90:91], v[166:167], v[208:209]
	v_pk_fma_f32 v[88:89], v[88:89], v[164:165], v[206:207]
	global_store_dwordx4 v219, v[88:91], s[10:11] offset:64
	v_pk_fma_f32 v[86:87], v[86:87], v[170:171], v[212:213]
	v_pk_fma_f32 v[84:85], v[84:85], v[168:169], v[210:211]
	global_store_dwordx4 v219, v[84:87], s[10:11] offset:512
	v_pk_fma_f32 v[82:83], v[82:83], v[174:175], v[216:217]
	v_pk_fma_f32 v[80:81], v[80:81], v[172:173], v[214:215]
	global_store_dwordx4 v219, v[80:83], s[10:11] offset:576
	v_lshrrev_b32_e32 v220, 1, v219
	v_mul_f32_e32 v202, v92, v186
	v_mul_f32_e32 v203, v93, v187
	v_mul_f32_e32 v204, v94, v188
	v_mul_f32_e32 v205, v95, v189
	v_mul_f32_e32 v221, v92, v92
	v_fmac_f32_e32 v221, v93, v93
	v_fmac_f32_e32 v221, v94, v94
	v_fmac_f32_e32 v221, v95, v95
	v_cvt_pk_bf16_f32 v202, v202, v203
	v_cvt_pk_bf16_f32 v203, v204, v205
	global_store_dwordx2 v220, v[202:203], s[14:15] offset:0
	v_mul_f32_e32 v206, v88, v190
	v_mul_f32_e32 v207, v89, v191
	v_mul_f32_e32 v208, v90, v192
	v_mul_f32_e32 v209, v91, v193
	v_fmac_f32_e32 v221, v88, v88
	v_fmac_f32_e32 v221, v89, v89
	v_fmac_f32_e32 v221, v90, v90
	v_fmac_f32_e32 v221, v91, v91
	v_cvt_pk_bf16_f32 v206, v206, v207
	v_cvt_pk_bf16_f32 v207, v208, v209
	global_store_dwordx2 v220, v[206:207], s[14:15] offset:32
	v_mul_f32_e32 v210, v84, v194
	v_mul_f32_e32 v211, v85, v195
	v_mul_f32_e32 v212, v86, v196
	v_mul_f32_e32 v213, v87, v197
	v_fmac_f32_e32 v221, v84, v84
	v_fmac_f32_e32 v221, v85, v85
	v_fmac_f32_e32 v221, v86, v86
	v_fmac_f32_e32 v221, v87, v87
	v_cvt_pk_bf16_f32 v210, v210, v211
	v_cvt_pk_bf16_f32 v211, v212, v213
	global_store_dwordx2 v220, v[210:211], s[14:15] offset:256
	v_mul_f32_e32 v214, v80, v198
	v_mul_f32_e32 v215, v81, v199
	v_mul_f32_e32 v216, v82, v200
	v_mul_f32_e32 v217, v83, v201
	v_fmac_f32_e32 v221, v80, v80
	v_fmac_f32_e32 v221, v81, v81
	v_fmac_f32_e32 v221, v82, v82
	v_fmac_f32_e32 v221, v83, v83
	v_cvt_pk_bf16_f32 v214, v214, v215
	v_cvt_pk_bf16_f32 v215, v216, v217
	global_store_dwordx2 v220, v[214:215], s[14:15] offset:288
	v_mov_b32_e32 v92, v221
	global_load_dwordx4 v[202:205], v218, s[46:47] offset:0
	global_load_dwordx4 v[206:209], v218, s[46:47] offset:64
	global_load_dwordx4 v[210:213], v218, s[46:47] offset:512
	global_load_dwordx4 v[214:217], v218, s[46:47] offset:576
	v_add_u32_e32 v218, 0x20000, v218
	v_add_u32_e32 v219, 0x20000, v219
	s_waitcnt vmcnt(12)
; __device__ __forceinline__ unsigned cvt_pk_bf16(float lo, float hi) { unsigned r; asm volatile("v_cvt_pk_bf16_f32 %0, %1, %2" : "=v"(r) : "v"(lo), "v"(hi)); return r; }
;     __device__ __forceinline__ void operator()(const gacc_t (&acc)[2][2][4][2], const Unit& u, int wr, int wc, int fr, int fq) const {
;     ...
;                     for (int n = 0; n < 2; ++n) { const int col = u.pn * 256 + bj * 128 + wc * 32 + n * 16 + 4 * fq;
;                         const f32x4 b = *(const f32x4*)(bp + col), g = *(const f32x4*)(gp + col); const gacc_t a = acc[ai][bj][m][n];
;                         f32x4 o; o.x = b.x + g.x * a[0]; o.y = b.y + g.y * a[1]; o.z = b.z + g.z * a[2]; o.w = b.w + g.w * a[3];
;                         *(f32x4*)(op + col) = o;
;                         if (hu) { const f32x4 gg = *(const f32x4*)(gn + col), sc = *(const f32x4*)(scl + mb * MODW + col);
;                             sq += (o.x * o.x + o.y * o.y) + (o.z * o.z + o.w * o.w);
;                             u32x2 w; w.x = pg8::cvt_pk_bf16(o.x * gg.x * (1.f + sc.x), o.y * gg.y * (1.f + sc.y)); w.y = pg8::cvt_pk_bf16(o.z * gg.z * (1.f + sc.z), o.w * gg.w * (1.f + sc.w));
;                             *(u32x2*)(hu + (size_t)row * D + col) = w; } }
	v_pk_fma_f32 v[78:79], v[78:79], v[162:163], v[144:145]
	v_pk_fma_f32 v[76:77], v[76:77], v[160:161], v[142:143]
	global_store_dwordx4 v219, v[76:79], s[10:11] offset:0
	v_pk_fma_f32 v[74:75], v[74:75], v[166:167], v[148:149]
	v_pk_fma_f32 v[72:73], v[72:73], v[164:165], v[146:147]
	global_store_dwordx4 v219, v[72:75], s[10:11] offset:64
	v_pk_fma_f32 v[70:71], v[70:71], v[170:171], v[178:179]
	v_pk_fma_f32 v[68:69], v[68:69], v[168:169], v[176:177]
	global_store_dwordx4 v219, v[68:71], s[10:11] offset:512
	v_pk_fma_f32 v[66:67], v[66:67], v[174:175], v[182:183]
	v_pk_fma_f32 v[64:65], v[64:65], v[172:173], v[180:181]
	global_store_dwordx4 v219, v[64:67], s[10:11] offset:576
	v_lshrrev_b32_e32 v220, 1, v219
	v_mul_f32_e32 v142, v76, v186
	v_mul_f32_e32 v143, v77, v187
	v_mul_f32_e32 v144, v78, v188
	v_mul_f32_e32 v145, v79, v189
	v_mul_f32_e32 v221, v76, v76
	v_fmac_f32_e32 v221, v77, v77
	v_fmac_f32_e32 v221, v78, v78
	v_fmac_f32_e32 v221, v79, v79
	v_cvt_pk_bf16_f32 v142, v142, v143
	v_cvt_pk_bf16_f32 v143, v144, v145
	global_store_dwordx2 v220, v[142:143], s[14:15] offset:0
	v_mul_f32_e32 v146, v72, v190
	v_mul_f32_e32 v147, v73, v191
	v_mul_f32_e32 v148, v74, v192
	v_mul_f32_e32 v149, v75, v193
	v_fmac_f32_e32 v221, v72, v72
	v_fmac_f32_e32 v221, v73, v73
	v_fmac_f32_e32 v221, v74, v74
	v_fmac_f32_e32 v221, v75, v75
	v_cvt_pk_bf16_f32 v146, v146, v147
	v_cvt_pk_bf16_f32 v147, v148, v149
	global_store_dwordx2 v220, v[146:147], s[14:15] offset:32
	v_mul_f32_e32 v176, v68, v194
	v_mul_f32_e32 v177, v69, v195
	v_mul_f32_e32 v178, v70, v196
	v_mul_f32_e32 v179, v71, v197
	v_fmac_f32_e32 v221, v68, v68
	v_fmac_f32_e32 v221, v69, v69
	v_fmac_f32_e32 v221, v70, v70
	v_fmac_f32_e32 v221, v71, v71
	v_cvt_pk_bf16_f32 v176, v176, v177
	v_cvt_pk_bf16_f32 v177, v178, v179
	global_store_dwordx2 v220, v[176:177], s[14:15] offset:256
	v_mul_f32_e32 v180, v64, v198
	v_mul_f32_e32 v181, v65, v199
	v_mul_f32_e32 v182, v66, v200
	v_mul_f32_e32 v183, v67, v201
	v_fmac_f32_e32 v221, v64, v64
	v_fmac_f32_e32 v221, v65, v65
	v_fmac_f32_e32 v221, v66, v66
	v_fmac_f32_e32 v221, v67, v67
	v_cvt_pk_bf16_f32 v180, v180, v181
	v_cvt_pk_bf16_f32 v181, v182, v183
	global_store_dwordx2 v220, v[180:181], s[14:15] offset:288
	v_mov_b32_e32 v76, v221
	global_load_dwordx4 v[142:145], v218, s[46:47] offset:0
	global_load_dwordx4 v[146:149], v218, s[46:47] offset:64
	global_load_dwordx4 v[176:179], v218, s[46:47] offset:512
	global_load_dwordx4 v[180:183], v218, s[46:47] offset:576
	v_add_u32_e32 v218, 0x20000, v218
	v_add_u32_e32 v219, 0xa0000, v219
	s_waitcnt vmcnt(12)
	v_pk_fma_f32 v[62:63], v[62:63], v[162:163], v[204:205]
	v_pk_fma_f32 v[60:61], v[60:61], v[160:161], v[202:203]
	global_store_dwordx4 v219, v[60:63], s[10:11] offset:0
	v_pk_fma_f32 v[58:59], v[58:59], v[166:167], v[208:209]
	v_pk_fma_f32 v[56:57], v[56:57], v[164:165], v[206:207]
	global_store_dwordx4 v219, v[56:59], s[10:11] offset:64
	v_pk_fma_f32 v[54:55], v[54:55], v[170:171], v[212:213]
	v_pk_fma_f32 v[52:53], v[52:53], v[168:169], v[210:211]
	global_store_dwordx4 v219, v[52:55], s[10:11] offset:512
	v_pk_fma_f32 v[50:51], v[50:51], v[174:175], v[216:217]
	v_pk_fma_f32 v[48:49], v[48:49], v[172:173], v[214:215]
	global_store_dwordx4 v219, v[48:51], s[10:11] offset:576
	v_lshrrev_b32_e32 v220, 1, v219
	v_mul_f32_e32 v202, v60, v186
	v_mul_f32_e32 v203, v61, v187
	v_mul_f32_e32 v204, v62, v188
	v_mul_f32_e32 v205, v63, v189
	v_mul_f32_e32 v221, v60, v60
	v_fmac_f32_e32 v221, v61, v61
	v_fmac_f32_e32 v221, v62, v62
	v_fmac_f32_e32 v221, v63, v63
	v_cvt_pk_bf16_f32 v202, v202, v203
	v_cvt_pk_bf16_f32 v203, v204, v205
	global_store_dwordx2 v220, v[202:203], s[14:15] offset:0
	v_mul_f32_e32 v206, v56, v190
	v_mul_f32_e32 v207, v57, v191
	v_mul_f32_e32 v208, v58, v192
	v_mul_f32_e32 v209, v59, v193
	v_fmac_f32_e32 v221, v56, v56
	v_fmac_f32_e32 v221, v57, v57
	v_fmac_f32_e32 v221, v58, v58
	v_fmac_f32_e32 v221, v59, v59
	v_cvt_pk_bf16_f32 v206, v206, v207
	v_cvt_pk_bf16_f32 v207, v208, v209
	global_store_dwordx2 v220, v[206:207], s[14:15] offset:32
	v_mul_f32_e32 v210, v52, v194
	v_mul_f32_e32 v211, v53, v195
	v_mul_f32_e32 v212, v54, v196
	v_mul_f32_e32 v213, v55, v197
	v_fmac_f32_e32 v221, v52, v52
	v_fmac_f32_e32 v221, v53, v53
	v_fmac_f32_e32 v221, v54, v54
	v_fmac_f32_e32 v221, v55, v55
	v_cvt_pk_bf16_f32 v210, v210, v211
	v_cvt_pk_bf16_f32 v211, v212, v213
	global_store_dwordx2 v220, v[210:211], s[14:15] offset:256
	v_mul_f32_e32 v214, v48, v198
	v_mul_f32_e32 v215, v49, v199
	v_mul_f32_e32 v216, v50, v200
	v_mul_f32_e32 v217, v51, v201
	v_fmac_f32_e32 v221, v48, v48
	v_fmac_f32_e32 v221, v49, v49
	v_fmac_f32_e32 v221, v50, v50
	v_fmac_f32_e32 v221, v51, v51
	v_cvt_pk_bf16_f32 v214, v214, v215
	v_cvt_pk_bf16_f32 v215, v216, v217
	global_store_dwordx2 v220, v[214:215], s[14:15] offset:288
	v_mov_b32_e32 v60, v221
	global_load_dwordx4 v[202:205], v218, s[46:47] offset:0
	global_load_dwordx4 v[206:209], v218, s[46:47] offset:64
	global_load_dwordx4 v[210:213], v218, s[46:47] offset:512
	global_load_dwordx4 v[214:217], v218, s[46:47] offset:576
	v_add_u32_e32 v218, 0x20000, v218
	v_add_u32_e32 v219, 0x20000, v219
	s_waitcnt vmcnt(12)
; __device__ __forceinline__ unsigned cvt_pk_bf16(float lo, float hi) { unsigned r; asm volatile("v_cvt_pk_bf16_f32 %0, %1, %2" : "=v"(r) : "v"(lo), "v"(hi)); return r; }
;     __device__ __forceinline__ void operator()(const gacc_t (&acc)[2][2][4][2], const Unit& u, int wr, int wc, int fr, int fq) const {
;     ...
;                     for (int n = 0; n < 2; ++n) { const int col = u.pn * 256 + bj * 128 + wc * 32 + n * 16 + 4 * fq;
;                         const f32x4 b = *(const f32x4*)(bp + col), g = *(const f32x4*)(gp + col); const gacc_t a = acc[ai][bj][m][n];
;                         f32x4 o; o.x = b.x + g.x * a[0]; o.y = b.y + g.y * a[1]; o.z = b.z + g.z * a[2]; o.w = b.w + g.w * a[3];
;                         *(f32x4*)(op + col) = o;
;                         if (hu) { const f32x4 gg = *(const f32x4*)(gn + col), sc = *(const f32x4*)(scl + mb * MODW + col);
;                             sq += (o.x * o.x + o.y * o.y) + (o.z * o.z + o.w * o.w);
;                             u32x2 w; w.x = pg8::cvt_pk_bf16(o.x * gg.x * (1.f + sc.x), o.y * gg.y * (1.f + sc.y)); w.y = pg8::cvt_pk_bf16(o.z * gg.z * (1.f + sc.z), o.w * gg.w * (1.f + sc.w));
;                             *(u32x2*)(hu + (size_t)row * D + col) = w; } }
	v_pk_fma_f32 v[46:47], v[46:47], v[162:163], v[144:145]
	v_pk_fma_f32 v[44:45], v[44:45], v[160:161], v[142:143]
	global_store_dwordx4 v219, v[44:47], s[10:11] offset:0
	v_pk_fma_f32 v[42:43], v[42:43], v[166:167], v[148:149]
	v_pk_fma_f32 v[40:41], v[40:41], v[164:165], v[146:147]
	global_store_dwordx4 v219, v[40:43], s[10:11] offset:64
	v_pk_fma_f32 v[38:39], v[38:39], v[170:171], v[178:179]
	v_pk_fma_f32 v[36:37], v[36:37], v[168:169], v[176:177]
	global_store_dwordx4 v219, v[36:39], s[10:11] offset:512
	v_pk_fma_f32 v[34:35], v[34:35], v[174:175], v[182:183]
	v_pk_fma_f32 v[32:33], v[32:33], v[172:173], v[180:181]
	global_store_dwordx4 v219, v[32:35], s[10:11] offset:576
	v_lshrrev_b32_e32 v220, 1, v219
	v_mul_f32_e32 v142, v44, v186
	v_mul_f32_e32 v143, v45, v187
	v_mul_f32_e32 v144, v46, v188
	v_mul_f32_e32 v145, v47, v189
	v_mul_f32_e32 v221, v44, v44
	v_fmac_f32_e32 v221, v45, v45
	v_fmac_f32_e32 v221, v46, v46
	v_fmac_f32_e32 v221, v47, v47
	v_cvt_pk_bf16_f32 v142, v142, v143
	v_cvt_pk_bf16_f32 v143, v144, v145
	global_store_dwordx2 v220, v[142:143], s[14:15] offset:0
	v_mul_f32_e32 v146, v40, v190
	v_mul_f32_e32 v147, v41, v191
	v_mul_f32_e32 v148, v42, v192
	v_mul_f32_e32 v149, v43, v193
	v_fmac_f32_e32 v221, v40, v40
	v_fmac_f32_e32 v221, v41, v41
	v_fmac_f32_e32 v221, v42, v42
	v_fmac_f32_e32 v221, v43, v43
	v_cvt_pk_bf16_f32 v146, v146, v147
	v_cvt_pk_bf16_f32 v147, v148, v149
	global_store_dwordx2 v220, v[146:147], s[14:15] offset:32
	v_mul_f32_e32 v176, v36, v194
	v_mul_f32_e32 v177, v37, v195
	v_mul_f32_e32 v178, v38, v196
	v_mul_f32_e32 v179, v39, v197
	v_fmac_f32_e32 v221, v36, v36
	v_fmac_f32_e32 v221, v37, v37
	v_fmac_f32_e32 v221, v38, v38
	v_fmac_f32_e32 v221, v39, v39
	v_cvt_pk_bf16_f32 v176, v176, v177
	v_cvt_pk_bf16_f32 v177, v178, v179
	global_store_dwordx2 v220, v[176:177], s[14:15] offset:256
	v_mul_f32_e32 v180, v32, v198
	v_mul_f32_e32 v181, v33, v199
	v_mul_f32_e32 v182, v34, v200
	v_mul_f32_e32 v183, v35, v201
	v_fmac_f32_e32 v221, v32, v32
	v_fmac_f32_e32 v221, v33, v33
	v_fmac_f32_e32 v221, v34, v34
	v_fmac_f32_e32 v221, v35, v35
	v_cvt_pk_bf16_f32 v180, v180, v181
	v_cvt_pk_bf16_f32 v181, v182, v183
	global_store_dwordx2 v220, v[180:181], s[14:15] offset:288
	v_mov_b32_e32 v44, v221
	global_load_dwordx4 v[142:145], v218, s[46:47] offset:0
	global_load_dwordx4 v[146:149], v218, s[46:47] offset:64
	global_load_dwordx4 v[176:179], v218, s[46:47] offset:512
	global_load_dwordx4 v[180:183], v218, s[46:47] offset:576
	v_add_u32_e32 v219, 0x20000, v219
	s_waitcnt vmcnt(12)
	v_pk_fma_f32 v[30:31], v[30:31], v[162:163], v[204:205]
	v_pk_fma_f32 v[28:29], v[28:29], v[160:161], v[202:203]
	global_store_dwordx4 v219, v[28:31], s[10:11] offset:0
	v_pk_fma_f32 v[26:27], v[26:27], v[166:167], v[208:209]
	v_pk_fma_f32 v[24:25], v[24:25], v[164:165], v[206:207]
	global_store_dwordx4 v219, v[24:27], s[10:11] offset:64
	v_pk_fma_f32 v[22:23], v[22:23], v[170:171], v[212:213]
	v_pk_fma_f32 v[20:21], v[20:21], v[168:169], v[210:211]
	global_store_dwordx4 v219, v[20:23], s[10:11] offset:512
	v_pk_fma_f32 v[18:19], v[18:19], v[174:175], v[216:217]
	v_pk_fma_f32 v[16:17], v[16:17], v[172:173], v[214:215]
	global_store_dwordx4 v219, v[16:19], s[10:11] offset:576
	v_lshrrev_b32_e32 v220, 1, v219
	v_mul_f32_e32 v202, v28, v186
	v_mul_f32_e32 v203, v29, v187
	v_mul_f32_e32 v204, v30, v188
	v_mul_f32_e32 v205, v31, v189
	v_mul_f32_e32 v221, v28, v28
	v_fmac_f32_e32 v221, v29, v29
	v_fmac_f32_e32 v221, v30, v30
	v_fmac_f32_e32 v221, v31, v31
	v_cvt_pk_bf16_f32 v202, v202, v203
	v_cvt_pk_bf16_f32 v203, v204, v205
	global_store_dwordx2 v220, v[202:203], s[14:15] offset:0
	v_mul_f32_e32 v206, v24, v190
	v_mul_f32_e32 v207, v25, v191
	v_mul_f32_e32 v208, v26, v192
	v_mul_f32_e32 v209, v27, v193
	v_fmac_f32_e32 v221, v24, v24
	v_fmac_f32_e32 v221, v25, v25
	v_fmac_f32_e32 v221, v26, v26
	v_fmac_f32_e32 v221, v27, v27
	v_cvt_pk_bf16_f32 v206, v206, v207
	v_cvt_pk_bf16_f32 v207, v208, v209
	global_store_dwordx2 v220, v[206:207], s[14:15] offset:32
	v_mul_f32_e32 v210, v20, v194
	v_mul_f32_e32 v211, v21, v195
	v_mul_f32_e32 v212, v22, v196
	v_mul_f32_e32 v213, v23, v197
	v_fmac_f32_e32 v221, v20, v20
	v_fmac_f32_e32 v221, v21, v21
	v_fmac_f32_e32 v221, v22, v22
	v_fmac_f32_e32 v221, v23, v23
	v_cvt_pk_bf16_f32 v210, v210, v211
	v_cvt_pk_bf16_f32 v211, v212, v213
	global_store_dwordx2 v220, v[210:211], s[14:15] offset:256
	v_mul_f32_e32 v214, v16, v198
	v_mul_f32_e32 v215, v17, v199
	v_mul_f32_e32 v216, v18, v200
	v_mul_f32_e32 v217, v19, v201
	v_fmac_f32_e32 v221, v16, v16
	v_fmac_f32_e32 v221, v17, v17
	v_fmac_f32_e32 v221, v18, v18
	v_fmac_f32_e32 v221, v19, v19
	v_cvt_pk_bf16_f32 v214, v214, v215
	v_cvt_pk_bf16_f32 v215, v216, v217
	global_store_dwordx2 v220, v[214:215], s[14:15] offset:288
	v_mov_b32_e32 v28, v221
	v_add_u32_e32 v219, 0x20000, v219
	s_waitcnt vmcnt(8)
; __device__ __forceinline__ unsigned cvt_pk_bf16(float lo, float hi) { unsigned r; asm volatile("v_cvt_pk_bf16_f32 %0, %1, %2" : "=v"(r) : "v"(lo), "v"(hi)); return r; }
;     __device__ __forceinline__ void operator()(const gacc_t (&acc)[2][2][4][2], const Unit& u, int wr, int wc, int fr, int fq) const {
;     ...
;                     for (int n = 0; n < 2; ++n) { const int col = u.pn * 256 + bj * 128 + wc * 32 + n * 16 + 4 * fq;
;                         const f32x4 b = *(const f32x4*)(bp + col), g = *(const f32x4*)(gp + col); const gacc_t a = acc[ai][bj][m][n];
;                         f32x4 o; o.x = b.x + g.x * a[0]; o.y = b.y + g.y * a[1]; o.z = b.z + g.z * a[2]; o.w = b.w + g.w * a[3];
;                         *(f32x4*)(op + col) = o;
;                         if (hu) { const f32x4 gg = *(const f32x4*)(gn + col), sc = *(const f32x4*)(scl + mb * MODW + col);
;                             sq += (o.x * o.x + o.y * o.y) + (o.z * o.z + o.w * o.w);
;                             u32x2 w; w.x = pg8::cvt_pk_bf16(o.x * gg.x * (1.f + sc.x), o.y * gg.y * (1.f + sc.y)); w.y = pg8::cvt_pk_bf16(o.z * gg.z * (1.f + sc.z), o.w * gg.w * (1.f + sc.w));
;                             *(u32x2*)(hu + (size_t)row * D + col) = w; } }
;                 if (hu) { sq += __shfl_xor(sq, 16); sq += __shfl_xor(sq, 32); if (fq == 0) __hip_atomic_fetch_add(ss + row, sq, __ATOMIC_RELAXED, __HIP_MEMORY_SCOPE_AGENT); } }
	v_pk_fma_f32 v[14:15], v[14:15], v[162:163], v[144:145]
	v_pk_fma_f32 v[12:13], v[12:13], v[160:161], v[142:143]
	global_store_dwordx4 v219, v[12:15], s[10:11] offset:0
	v_pk_fma_f32 v[10:11], v[10:11], v[166:167], v[148:149]
	v_pk_fma_f32 v[8:9], v[8:9], v[164:165], v[146:147]
	global_store_dwordx4 v219, v[8:11], s[10:11] offset:64
	v_pk_fma_f32 v[6:7], v[6:7], v[170:171], v[178:179]
	v_pk_fma_f32 v[4:5], v[4:5], v[168:169], v[176:177]
	global_store_dwordx4 v219, v[4:7], s[10:11] offset:512
	v_pk_fma_f32 v[2:3], v[2:3], v[174:175], v[182:183]
	v_pk_fma_f32 v[0:1], v[0:1], v[172:173], v[180:181]
	global_store_dwordx4 v219, v[0:3], s[10:11] offset:576
	v_lshrrev_b32_e32 v220, 1, v219
	v_mul_f32_e32 v142, v12, v186
	v_mul_f32_e32 v143, v13, v187
	v_mul_f32_e32 v144, v14, v188
	v_mul_f32_e32 v145, v15, v189
	v_mul_f32_e32 v221, v12, v12
	v_fmac_f32_e32 v221, v13, v13
	v_fmac_f32_e32 v221, v14, v14
	v_fmac_f32_e32 v221, v15, v15
	v_cvt_pk_bf16_f32 v142, v142, v143
	v_cvt_pk_bf16_f32 v143, v144, v145
	global_store_dwordx2 v220, v[142:143], s[14:15] offset:0
	v_mul_f32_e32 v146, v8, v190
	v_mul_f32_e32 v147, v9, v191
	v_mul_f32_e32 v148, v10, v192
	v_mul_f32_e32 v149, v11, v193
	v_fmac_f32_e32 v221, v8, v8
	v_fmac_f32_e32 v221, v9, v9
	v_fmac_f32_e32 v221, v10, v10
	v_fmac_f32_e32 v221, v11, v11
	v_cvt_pk_bf16_f32 v146, v146, v147
	v_cvt_pk_bf16_f32 v147, v148, v149
	global_store_dwordx2 v220, v[146:147], s[14:15] offset:32
	v_mul_f32_e32 v176, v4, v194
	v_mul_f32_e32 v177, v5, v195
	v_mul_f32_e32 v178, v6, v196
	v_mul_f32_e32 v179, v7, v197
	v_fmac_f32_e32 v221, v4, v4
	v_fmac_f32_e32 v221, v5, v5
	v_fmac_f32_e32 v221, v6, v6
	v_fmac_f32_e32 v221, v7, v7
	v_cvt_pk_bf16_f32 v176, v176, v177
	v_cvt_pk_bf16_f32 v177, v178, v179
	global_store_dwordx2 v220, v[176:177], s[14:15] offset:256
	v_mul_f32_e32 v180, v0, v198
	v_mul_f32_e32 v181, v1, v199
	v_mul_f32_e32 v182, v2, v200
	v_mul_f32_e32 v183, v3, v201
	v_fmac_f32_e32 v221, v0, v0
	v_fmac_f32_e32 v221, v1, v1
	v_fmac_f32_e32 v221, v2, v2
	v_fmac_f32_e32 v221, v3, v3
	v_cvt_pk_bf16_f32 v180, v180, v181
	v_cvt_pk_bf16_f32 v181, v182, v183
	global_store_dwordx2 v220, v[180:181], s[14:15] offset:288
	v_mov_b32_e32 v12, v221
	v_xor_b32_e32 v220, 16, v158
	v_lshlrev_b32_e32 v220, 2, v220
	v_xor_b32_e32 v221, 32, v158
	v_lshlrev_b32_e32 v221, 2, v221
	ds_bpermute_b32 v202, v220, v124
	ds_bpermute_b32 v203, v220, v108
	ds_bpermute_b32 v204, v220, v92
	ds_bpermute_b32 v205, v220, v76
	ds_bpermute_b32 v206, v220, v60
	ds_bpermute_b32 v207, v220, v44
	ds_bpermute_b32 v208, v220, v28
	ds_bpermute_b32 v209, v220, v12
	s_waitcnt lgkmcnt(0)
	v_add_f32_e32 v124, v124, v202
	v_add_f32_e32 v108, v108, v203
	v_add_f32_e32 v92, v92, v204
	v_add_f32_e32 v76, v76, v205
	v_add_f32_e32 v60, v60, v206
	v_add_f32_e32 v44, v44, v207
	v_add_f32_e32 v28, v28, v208
	v_add_f32_e32 v12, v12, v209
	ds_bpermute_b32 v202, v221, v124
	ds_bpermute_b32 v203, v221, v108
	ds_bpermute_b32 v204, v221, v92
	ds_bpermute_b32 v205, v221, v76
	ds_bpermute_b32 v206, v221, v60
	ds_bpermute_b32 v207, v221, v44
	ds_bpermute_b32 v208, v221, v28
	ds_bpermute_b32 v209, v221, v12
	v_add_u32_e32 v220, s48, v152
	v_lshlrev_b32_e32 v220, 2, v220
	s_waitcnt lgkmcnt(0)
	v_add_f32_e32 v124, v124, v202
	v_add_f32_e32 v108, v108, v203
	v_add_f32_e32 v92, v92, v204
	v_add_f32_e32 v76, v76, v205
	v_add_f32_e32 v60, v60, v206
	v_add_f32_e32 v44, v44, v207
	v_add_f32_e32 v28, v28, v208
	v_add_f32_e32 v12, v12, v209
	s_and_saveexec_b64 s[44:45], s[2:3]
	global_atomic_add_f32 v220, v124, s[28:29] offset:0
	global_atomic_add_f32 v220, v108, s[28:29] offset:64
	global_atomic_add_f32 v220, v92, s[28:29] offset:128
	global_atomic_add_f32 v220, v76, s[28:29] offset:192
	global_atomic_add_f32 v220, v60, s[28:29] offset:512
	global_atomic_add_f32 v220, v44, s[28:29] offset:576
	global_atomic_add_f32 v220, v28, s[28:29] offset:640
	global_atomic_add_f32 v220, v12, s[28:29] offset:704
	s_mov_b64 exec, s[44:45]
	s_and_b64 vcc, exec, s[4:5]
	s_mov_b64 s[4:5], -1
	s_cbranch_vccnz .LBB0_820
	s_andn2_b64 vcc, exec, s[0:1]
	s_cbranch_vccnz .LBB0_819
	s_barrier
	s_branch .LBB0_819

; __device__ __forceinline__ unsigned cvt_pk_bf16(float lo, float hi) { unsigned r; asm volatile("v_cvt_pk_bf16_f32 %0, %1, %2" : "=v"(r) : "v"(lo), "v"(hi)); return r; }
; __device__ __forceinline__ float siluf(float v) { return v * __builtin_amdgcn_rcpf(1.0f + __expf(-v)); }
;     __device__ __forceinline__ void operator()(const gacc_t (&acc)[2][2][4][2], const Unit& u, int wr, int wc, int fr, int fq) const {
;         const int row0 = u.pm * 256 + wr * 64 + fr, col0 = u.pn * 128 + wc * 32 + 8 * fq;
;         const int ra = u.pm * 256; const float* shp = shw + (ra < ML ? (ra >> 11) : 8) * (2 * FF) + u.pn * 256 + wc * 32 + 8 * fq;
;         const f32x4 sg0 = *(const f32x4*)shp, sg1 = *(const f32x4*)(shp + 4), su0 = *(const f32x4*)(shp + 128), su1 = *(const f32x4*)(shp + 132);
; #pragma unroll
;         for (int ai = 0; ai < 2; ++ai)
; #pragma unroll
;             for (int m = 0; m < 4; ++m) { bf16_t* rowp = O + (size_t)(row0 + ai * 128 + m * 16) * FF + col0;
;                 const float rs = 1.0f / sqrtf(ss[row0 + ai * 128 + m * 16] * (1.0f / D) + NEPS);
;                 const gacc_t a0 = acc[ai][0][m][0], a1 = acc[ai][0][m][1], b0 = acc[ai][1][m][0], b1 = acc[ai][1][m][1];
;                 const float g0[4] = {a0[0] * rs + sg0.x, a0[1] * rs + sg0.y, a0[2] * rs + sg0.z, a0[3] * rs + sg0.w}, g1[4] = {a1[0] * rs + sg1.x, a1[1] * rs + sg1.y, a1[2] * rs + sg1.z, a1[3] * rs + sg1.w};
;                 const float u0[4] = {b0[0] * rs + su0.x, b0[1] * rs + su0.y, b0[2] * rs + su0.z, b0[3] * rs + su0.w}, u1[4] = {b1[0] * rs + su1.x, b1[1] * rs + su1.y, b1[2] * rs + su1.z, b1[3] * rs + su1.w};
;                 u32x4 w;
;                 w.x = pg8::cvt_pk_bf16(siluf(g0[0]) * u0[0], siluf(g0[1]) * u0[1]); w.y = pg8::cvt_pk_bf16(siluf(g0[2]) * u0[2], siluf(g0[3]) * u0[3]);
;                 w.z = pg8::cvt_pk_bf16(siluf(g1[0]) * u1[0], siluf(g1[1]) * u1[1]); w.w = pg8::cvt_pk_bf16(siluf(g1[2]) * u1[2], siluf(g1[3]) * u1[3]);
;                 *(u32x4*)rowp = w; }
.LBB0_1601:
	v_lshl_add_u32 v152, s0, 8, v160
	v_ashrrev_i32_e32 v153, 31, v152
	v_lshl_add_u64 v[158:159], v[152:153], 2, s[8:9]
	s_min_i32 s0, s0, 64
	global_load_dword v153, v[158:159], off
	global_load_dword v190, v[158:159], off offset:64
	global_load_dword v191, v[158:159], off offset:128
	global_load_dword v192, v[158:159], off offset:192
	global_load_dword v193, v[158:159], off offset:512
	global_load_dword v194, v[158:159], off offset:576
	global_load_dword v195, v[158:159], off offset:640
	global_load_dword v196, v[158:159], off offset:704
	s_lshr_b32 s0, s0, 3
	s_mul_i32 s22, s0, 0x2c00
	s_ashr_i32 s23, s22, 31
	s_lshl_b64 s[22:23], s[22:23], 2
	s_add_u32 s0, s42, s22
	s_addc_u32 s15, s43, s23
	s_lshl_b32 s22, s1, 8
	s_ashr_i32 s23, s22, 31
	s_lshl_b64 s[22:23], s[22:23], 2
	s_add_u32 s0, s0, s22
	s_addc_u32 s15, s15, s23
	s_add_u32 s22, s0, s51
	s_addc_u32 s23, s15, 0
	global_load_dwordx4 v[170:173], v166, s[22:23] offset:512
	global_load_dwordx4 v[68:71], v166, s[22:23]
	global_load_dwordx4 v[174:177], v166, s[22:23] offset:528
	global_load_dwordx4 v[64:67], v166, s[22:23] offset:16
	v_mov_b32_e32 v182, v128
	v_mov_b32_e32 v183, v120
	v_mov_b32_e32 v120, v129
	v_mov_b32_e32 v186, v130
	v_lshl_or_b32 v156, s1, 7, v162
	v_mov_b64_e32 v[154:155], s[6:7]
	v_ashrrev_i32_e32 v157, 31, v156
	v_mov_b32_e32 v178, v132
	v_mov_b32_e32 v179, v124
	v_mov_b32_e32 v124, v133
	v_lshlrev_b64 v[132:133], 1, v[156:157]
	v_mov_b32_e32 v187, v122
	v_mov_b32_e32 v122, v131
	v_mov_b32_e32 v180, v134
	v_mov_b32_e32 v181, v126
	v_mov_b32_e32 v126, v135
	s_waitcnt vmcnt(0)
	v_fmamk_f32 v128, v153, 0x3a000000, v167
	v_mul_f32_e32 v129, 0x4f800000, v128
	v_cmp_gt_f32_e32 vcc, s52, v128
	v_mov_b32_e32 v156, v176
	s_nop 0
	v_cndmask_b32_e32 v153, v128, v129, vcc
	v_sqrt_f32_e32 v130, v153
	v_mad_i64_i32 v[128:129], s[0:1], v152, s50, v[154:155]
	v_lshl_add_u64 v[188:189], v[128:129], 0, v[132:133]
	v_add_u32_e32 v128, -1, v130
	v_add_u32_e32 v129, 1, v130
	v_fma_f32 v131, -v128, v130, v153
	v_fma_f32 v134, -v129, v130, v153
	v_cmp_ge_f32_e64 s[0:1], 0, v131
	v_mov_b32_e32 v157, v66
	v_mov_b32_e32 v131, v70
	v_cndmask_b32_e64 v128, v130, v128, s[0:1]
	v_cmp_lt_f32_e64 s[0:1], 0, v134
	v_mov_b32_e32 v130, v172
	v_mov_b32_e32 v70, v173
	v_cndmask_b32_e64 v169, v128, v129, s[0:1]
	v_mul_f32_e32 v66, 0x37800000, v169
	v_cndmask_b32_e32 v66, v169, v66, vcc
	v_cmp_class_f32_e32 vcc, v153, v168
	v_mov_b32_e32 v128, v170
	v_mov_b32_e32 v129, v68
	v_cndmask_b32_e32 v153, v66, v153, vcc
	v_div_scale_f32 v169, s[0:1], v153, v153, 1.0
	v_rcp_f32_e32 v170, v169
	v_mov_b32_e32 v68, v171
	v_div_scale_f32 v171, vcc, 1.0, v153, 1.0
	v_fma_f32 v172, -v169, v170, 1.0
	v_fmac_f32_e32 v170, v172, v170
	v_mul_f32_e32 v172, v171, v170
	v_fma_f32 v173, -v169, v172, v171
	v_fmac_f32_e32 v172, v173, v170
	v_fma_f32 v169, -v169, v172, v171
	v_div_fmas_f32 v169, v169, v170, v172
	v_div_fixup_f32 v170, v169, v153, 1.0
	v_mov_b32_e32 v135, v64
	v_mov_b32_e32 v64, v175
	v_pk_fma_f32 v[124:125], v[124:125], v[170:171], v[68:69] op_sel_hi:[1,0,1]
	v_pk_fma_f32 v[172:173], v[178:179], v[170:171], v[128:129] op_sel_hi:[1,0,1]
	v_pk_fma_f32 v[178:179], v[120:121], v[170:171], v[64:65] op_sel_hi:[1,0,1]
	v_mul_f32_e32 v121, 0xbfb8aa3b, v125
	v_exp_f32_e32 v121, v121
	v_mov_b32_e32 v134, v174
	v_mov_b32_e32 v66, v177
	v_pk_fma_f32 v[126:127], v[126:127], v[170:171], v[70:71] op_sel_hi:[1,0,1]
	v_pk_fma_f32 v[174:175], v[180:181], v[170:171], v[130:131] op_sel_hi:[1,0,1]
	v_pk_fma_f32 v[176:177], v[182:183], v[170:171], v[134:135] op_sel_hi:[1,0,1]
	v_pk_fma_f32 v[180:181], v[186:187], v[170:171], v[156:157] op_sel_hi:[1,0,1]
	v_pk_fma_f32 v[170:171], v[122:123], v[170:171], v[66:67] op_sel_hi:[1,0,1]
	v_mul_f32_e32 v120, 0xbfb8aa3b, v173
	v_mul_f32_e32 v123, 0xbfb8aa3b, v127
	v_mul_f32_e32 v122, 0xbfb8aa3b, v175
	v_exp_f32_e32 v120, v120
	v_exp_f32_e32 v123, v123
	v_mul_f32_e32 v169, 0xbfb8aa3b, v179
	v_exp_f32_e32 v122, v122
	v_add_f32_e32 v121, 1.0, v121
	v_exp_f32_e32 v169, v169
	v_rcp_f32_e32 v121, v121
	v_add_f32_e32 v120, 1.0, v120
	v_add_f32_e32 v123, 1.0, v123
	v_add_f32_e32 v122, 1.0, v122
	v_rcp_f32_e32 v120, v120
	v_rcp_f32_e32 v123, v123
	v_add_f32_e32 v169, 1.0, v169
	v_rcp_f32_e32 v122, v122
	v_mul_f32_e32 v121, v125, v121
	v_mul_f32_e32 v121, v124, v121
	v_rcp_f32_e32 v124, v169
	v_mul_f32_e32 v153, 0xbfb8aa3b, v177
	v_mul_f32_e32 v120, v173, v120
	v_mul_f32_e32 v123, v127, v123
	v_exp_f32_e32 v153, v153
	v_mul_f32_e32 v122, v175, v122
	v_mul_f32_e32 v120, v172, v120
	v_mul_f32_e32 v123, v126, v123
	v_mul_f32_e32 v122, v174, v122
	v_cvt_pk_bf16_f32 v120, v120, v121
	v_cvt_pk_bf16_f32 v121, v122, v123
	v_mul_f32_e32 v123, v179, v124
	v_mul_f32_e32 v124, 0xbfb8aa3b, v181
	v_exp_f32_e32 v124, v124
	v_mul_f32_e32 v125, 0xbfb8aa3b, v171
	v_exp_f32_e32 v125, v125
	v_add_f32_e32 v153, 1.0, v153
	v_rcp_f32_e32 v153, v153
	v_add_f32_e32 v124, 1.0, v124
	v_rcp_f32_e32 v124, v124
	v_add_f32_e32 v125, 1.0, v125
	v_rcp_f32_e32 v125, v125
	v_mul_f32_e32 v122, v177, v153
	v_mul_f32_e32 v122, v176, v122
	v_mul_f32_e32 v123, v178, v123
	v_cvt_pk_bf16_f32 v122, v122, v123
	v_mul_f32_e32 v123, v181, v124
	v_mul_f32_e32 v123, v180, v123
	v_mul_f32_e32 v124, v171, v125
	v_mul_f32_e32 v124, v170, v124
	v_cvt_pk_bf16_f32 v123, v123, v124
	global_store_dwordx4 v[188:189], v[120:123], off
	s_nop 1
	v_or_b32_e32 v120, 16, v152
	v_ashrrev_i32_e32 v121, 31, v120
	v_lshl_add_u64 v[122:123], v[120:121], 2, s[8:9]
	s_nop 1
	v_mov_b32_e32 v121, v190
	v_mov_b32_e32 v123, v112
	v_mov_b32_e32 v112, v117
	v_mov_b32_e32 v117, v114
	v_mov_b32_e32 v114, v119
	v_mov_b32_e32 v119, v104
	v_mov_b32_e32 v104, v109
; __device__ __forceinline__ unsigned cvt_pk_bf16(float lo, float hi) { unsigned r; asm volatile("v_cvt_pk_bf16_f32 %0, %1, %2" : "=v"(r) : "v"(lo), "v"(hi)); return r; }
; __device__ __forceinline__ float siluf(float v) { return v * __builtin_amdgcn_rcpf(1.0f + __expf(-v)); }
;     __device__ __forceinline__ void operator()(const gacc_t (&acc)[2][2][4][2], const Unit& u, int wr, int wc, int fr, int fq) const {
;     ...
;             for (int m = 0; m < 4; ++m) { bf16_t* rowp = O + (size_t)(row0 + ai * 128 + m * 16) * FF + col0;
;                 const float rs = 1.0f / sqrtf(ss[row0 + ai * 128 + m * 16] * (1.0f / D) + NEPS);
;                 const gacc_t a0 = acc[ai][0][m][0], a1 = acc[ai][0][m][1], b0 = acc[ai][1][m][0], b1 = acc[ai][1][m][1];
;                 const float g0[4] = {a0[0] * rs + sg0.x, a0[1] * rs + sg0.y, a0[2] * rs + sg0.z, a0[3] * rs + sg0.w}, g1[4] = {a1[0] * rs + sg1.x, a1[1] * rs + sg1.y, a1[2] * rs + sg1.z, a1[3] * rs + sg1.w};
;                 const float u0[4] = {b0[0] * rs + su0.x, b0[1] * rs + su0.y, b0[2] * rs + su0.z, b0[3] * rs + su0.w}, u1[4] = {b1[0] * rs + su1.x, b1[1] * rs + su1.y, b1[2] * rs + su1.z, b1[3] * rs + su1.w};
;                 u32x4 w;
;                 w.x = pg8::cvt_pk_bf16(siluf(g0[0]) * u0[0], siluf(g0[1]) * u0[1]); w.y = pg8::cvt_pk_bf16(siluf(g0[2]) * u0[2], siluf(g0[3]) * u0[3]);
;                 w.z = pg8::cvt_pk_bf16(siluf(g1[0]) * u1[0], siluf(g1[1]) * u1[1]); w.w = pg8::cvt_pk_bf16(siluf(g1[2]) * u1[2], siluf(g1[3]) * u1[3]);
;                 *(u32x4*)rowp = w; }
	v_mov_b32_e32 v109, v106
	v_mov_b32_e32 v122, v116
	v_mov_b32_e32 v116, v118
	v_mov_b32_e32 v118, v108
	v_mov_b32_e32 v108, v110
	v_fmamk_f32 v106, v121, 0x3a000000, v167
	v_mul_f32_e32 v110, 0x4f800000, v106
	v_cmp_gt_f32_e32 vcc, s52, v106
	s_nop 1
	v_cndmask_b32_e32 v121, v106, v110, vcc
	v_sqrt_f32_e32 v124, v121
	v_mov_b32_e32 v106, v111
	v_mad_i64_i32 v[110:111], s[0:1], v120, s50, v[154:155]
	v_add_u32_e32 v120, -1, v124
	v_add_u32_e32 v125, 1, v124
	v_fma_f32 v126, -v120, v124, v121
	v_fma_f32 v127, -v125, v124, v121
	v_cmp_ge_f32_e64 s[0:1], 0, v126
	v_lshl_add_u64 v[110:111], v[110:111], 0, v[132:133]
	s_nop 0
	v_cndmask_b32_e64 v120, v124, v120, s[0:1]
	v_cmp_lt_f32_e64 s[0:1], 0, v127
	s_nop 1
	v_cndmask_b32_e64 v120, v120, v125, s[0:1]
	v_mul_f32_e32 v124, 0x37800000, v120
	v_cndmask_b32_e32 v120, v120, v124, vcc
	v_cmp_class_f32_e32 vcc, v121, v168
	s_nop 1
	v_cndmask_b32_e32 v120, v120, v121, vcc
	v_div_scale_f32 v121, s[0:1], v120, v120, 1.0
	v_rcp_f32_e32 v124, v121
	v_div_scale_f32 v125, vcc, 1.0, v120, 1.0
	v_fma_f32 v126, -v121, v124, 1.0
	v_fmac_f32_e32 v124, v126, v124
	v_mul_f32_e32 v126, v125, v124
	v_fma_f32 v127, -v121, v126, v125
	v_fmac_f32_e32 v126, v127, v124
	v_fma_f32 v121, -v121, v126, v125
	v_div_fmas_f32 v121, v121, v124, v126
	v_div_fixup_f32 v120, v121, v120, 1.0
	v_pk_fma_f32 v[122:123], v[122:123], v[120:121], v[128:129] op_sel_hi:[1,0,1]
	v_pk_fma_f32 v[112:113], v[112:113], v[120:121], v[68:69] op_sel_hi:[1,0,1]
	v_pk_fma_f32 v[116:117], v[116:117], v[120:121], v[130:131] op_sel_hi:[1,0,1]
	v_pk_fma_f32 v[114:115], v[114:115], v[120:121], v[70:71] op_sel_hi:[1,0,1]
	v_pk_fma_f32 v[118:119], v[118:119], v[120:121], v[134:135] op_sel_hi:[1,0,1]
	v_pk_fma_f32 v[104:105], v[104:105], v[120:121], v[64:65] op_sel_hi:[1,0,1]
	v_pk_fma_f32 v[108:109], v[108:109], v[120:121], v[156:157] op_sel_hi:[1,0,1]
	v_pk_fma_f32 v[120:121], v[106:107], v[120:121], v[66:67] op_sel_hi:[1,0,1]
	v_mul_f32_e32 v106, 0xbfb8aa3b, v123
	v_mul_f32_e32 v107, 0xbfb8aa3b, v113
	v_mul_f32_e32 v124, 0xbfb8aa3b, v117
	v_mul_f32_e32 v125, 0xbfb8aa3b, v115
	v_mul_f32_e32 v127, 0xbfb8aa3b, v105
	v_exp_f32_e32 v106, v106
	v_exp_f32_e32 v107, v107
	v_exp_f32_e32 v124, v124
	v_exp_f32_e32 v125, v125
	v_exp_f32_e32 v127, v127
	v_add_f32_e32 v106, 1.0, v106
	v_add_f32_e32 v107, 1.0, v107
	v_mul_f32_e32 v153, 0xbfb8aa3b, v109
	v_add_f32_e32 v124, 1.0, v124
	v_add_f32_e32 v125, 1.0, v125
	v_add_f32_e32 v127, 1.0, v127
	v_rcp_f32_e32 v106, v106
	v_rcp_f32_e32 v107, v107
	v_mul_f32_e32 v126, 0xbfb8aa3b, v119
	v_mul_f32_e32 v169, 0xbfb8aa3b, v121
	v_exp_f32_e32 v153, v153
	v_rcp_f32_e32 v124, v124
	v_rcp_f32_e32 v125, v125
	v_rcp_f32_e32 v127, v127
	v_exp_f32_e32 v126, v126
	v_exp_f32_e32 v169, v169
	v_mul_f32_e32 v106, v123, v106
	v_mul_f32_e32 v107, v113, v107
	v_add_f32_e32 v153, 1.0, v153
	v_mul_f32_e32 v113, v117, v124
	v_mul_f32_e32 v115, v115, v125
	v_mul_f32_e32 v105, v105, v127
	v_mul_f32_e32 v106, v122, v106
	v_mul_f32_e32 v107, v112, v107
	v_add_f32_e32 v126, 1.0, v126
	v_mul_f32_e32 v112, v116, v113
	v_mul_f32_e32 v113, v114, v115
	v_mul_f32_e32 v115, v104, v105
	v_cvt_pk_bf16_f32 v104, v106, v107
	v_rcp_f32_e32 v107, v153
	v_add_f32_e32 v106, 1.0, v169
	v_rcp_f32_e32 v126, v126
	v_cvt_pk_bf16_f32 v105, v112, v113
	v_rcp_f32_e32 v112, v106
	v_mul_f32_e32 v107, v109, v107
	v_mul_f32_e32 v117, v119, v126
	v_mul_f32_e32 v107, v108, v107
	v_mul_f32_e32 v108, v121, v112
	v_mul_f32_e32 v114, v118, v117
	v_cvt_pk_bf16_f32 v106, v114, v115
	v_mul_f32_e32 v108, v120, v108
	v_cvt_pk_bf16_f32 v107, v107, v108
	global_store_dwordx4 v[110:111], v[104:107], off
	s_nop 1
	v_or_b32_e32 v104, 32, v152
	v_ashrrev_i32_e32 v105, 31, v104
	v_lshl_add_u64 v[106:107], v[104:105], 2, s[8:9]
	s_nop 1
	v_mov_b32_e32 v105, v191
	v_mov_b32_e32 v107, v92
	v_mov_b32_e32 v92, v101
	v_mov_b32_e32 v101, v94
	v_mov_b32_e32 v94, v103
	v_mov_b32_e32 v103, v88
	v_mov_b32_e32 v88, v97
	v_mov_b32_e32 v97, v90
	v_mov_b32_e32 v90, v99
	v_mov_b32_e32 v106, v100
	v_mov_b32_e32 v100, v102
	v_mov_b32_e32 v102, v96
	v_mov_b32_e32 v96, v98
	v_or_b32_e32 v98, 48, v152
	v_fmamk_f32 v99, v105, 0x3a000000, v167
	v_mul_f32_e32 v105, 0x4f800000, v99
	v_cmp_gt_f32_e32 vcc, s52, v99
	s_nop 1
	v_cndmask_b32_e32 v108, v99, v105, vcc
	v_sqrt_f32_e32 v109, v108
	v_mad_i64_i32 v[104:105], s[0:1], v104, s50, v[154:155]
	v_ashrrev_i32_e32 v99, 31, v98
	v_add_u32_e32 v110, -1, v109
	v_add_u32_e32 v111, 1, v109
	v_fma_f32 v112, -v110, v109, v108
	v_fma_f32 v113, -v111, v109, v108
	v_cmp_ge_f32_e64 s[0:1], 0, v112
	v_lshl_add_u64 v[104:105], v[104:105], 0, v[132:133]
	s_nop 0
	v_cndmask_b32_e64 v109, v109, v110, s[0:1]
	v_cmp_lt_f32_e64 s[0:1], 0, v113
	s_nop 1
	v_cndmask_b32_e64 v109, v109, v111, s[0:1]
	v_mul_f32_e32 v110, 0x37800000, v109
	v_cndmask_b32_e32 v109, v109, v110, vcc
	v_cmp_class_f32_e32 vcc, v108, v168
	s_nop 1
	v_cndmask_b32_e32 v108, v109, v108, vcc
	v_div_scale_f32 v109, s[0:1], v108, v108, 1.0
	v_rcp_f32_e32 v110, v109
	v_div_scale_f32 v111, vcc, 1.0, v108, 1.0
	v_fma_f32 v112, -v109, v110, 1.0
	v_fmac_f32_e32 v110, v112, v110
	v_mul_f32_e32 v112, v111, v110
	v_fma_f32 v113, -v109, v112, v111
	v_fmac_f32_e32 v112, v113, v110
	v_fma_f32 v109, -v109, v112, v111
	v_div_fmas_f32 v109, v109, v110, v112
	v_div_fixup_f32 v108, v109, v108, 1.0
	v_pk_fma_f32 v[106:107], v[106:107], v[108:109], v[128:129] op_sel_hi:[1,0,1]
	v_pk_fma_f32 v[92:93], v[92:93], v[108:109], v[68:69] op_sel_hi:[1,0,1]
	v_pk_fma_f32 v[100:101], v[100:101], v[108:109], v[130:131] op_sel_hi:[1,0,1]
	v_pk_fma_f32 v[94:95], v[94:95], v[108:109], v[70:71] op_sel_hi:[1,0,1]
	v_pk_fma_f32 v[88:89], v[88:89], v[108:109], v[64:65] op_sel_hi:[1,0,1]
; __device__ __forceinline__ unsigned cvt_pk_bf16(float lo, float hi) { unsigned r; asm volatile("v_cvt_pk_bf16_f32 %0, %1, %2" : "=v"(r) : "v"(lo), "v"(hi)); return r; }
; __device__ __forceinline__ float siluf(float v) { return v * __builtin_amdgcn_rcpf(1.0f + __expf(-v)); }
;     __device__ __forceinline__ void operator()(const gacc_t (&acc)[2][2][4][2], const Unit& u, int wr, int wc, int fr, int fq) const {
;     ...
;             for (int m = 0; m < 4; ++m) { bf16_t* rowp = O + (size_t)(row0 + ai * 128 + m * 16) * FF + col0;
;                 const float rs = 1.0f / sqrtf(ss[row0 + ai * 128 + m * 16] * (1.0f / D) + NEPS);
;                 const gacc_t a0 = acc[ai][0][m][0], a1 = acc[ai][0][m][1], b0 = acc[ai][1][m][0], b1 = acc[ai][1][m][1];
;                 const float g0[4] = {a0[0] * rs + sg0.x, a0[1] * rs + sg0.y, a0[2] * rs + sg0.z, a0[3] * rs + sg0.w}, g1[4] = {a1[0] * rs + sg1.x, a1[1] * rs + sg1.y, a1[2] * rs + sg1.z, a1[3] * rs + sg1.w};
;                 const float u0[4] = {b0[0] * rs + su0.x, b0[1] * rs + su0.y, b0[2] * rs + su0.z, b0[3] * rs + su0.w}, u1[4] = {b1[0] * rs + su1.x, b1[1] * rs + su1.y, b1[2] * rs + su1.z, b1[3] * rs + su1.w};
;                 u32x4 w;
;                 w.x = pg8::cvt_pk_bf16(siluf(g0[0]) * u0[0], siluf(g0[1]) * u0[1]); w.y = pg8::cvt_pk_bf16(siluf(g0[2]) * u0[2], siluf(g0[3]) * u0[3]);
;                 w.z = pg8::cvt_pk_bf16(siluf(g1[0]) * u1[0], siluf(g1[1]) * u1[1]); w.w = pg8::cvt_pk_bf16(siluf(g1[2]) * u1[2], siluf(g1[3]) * u1[3]);
;                 *(u32x4*)rowp = w; }
	v_pk_fma_f32 v[90:91], v[90:91], v[108:109], v[66:67] op_sel_hi:[1,0,1]
	v_pk_fma_f32 v[102:103], v[102:103], v[108:109], v[134:135] op_sel_hi:[1,0,1]
	v_pk_fma_f32 v[96:97], v[96:97], v[108:109], v[156:157] op_sel_hi:[1,0,1]
	v_mul_f32_e32 v108, 0xbfb8aa3b, v107
	v_mul_f32_e32 v109, 0xbfb8aa3b, v93
	v_mul_f32_e32 v110, 0xbfb8aa3b, v101
	v_mul_f32_e32 v111, 0xbfb8aa3b, v95
	v_mul_f32_e32 v113, 0xbfb8aa3b, v89
	v_mul_f32_e32 v115, 0xbfb8aa3b, v91
	v_mul_f32_e32 v112, 0xbfb8aa3b, v103
	v_mul_f32_e32 v114, 0xbfb8aa3b, v97
	v_exp_f32_e32 v108, v108
	v_exp_f32_e32 v109, v109
	v_exp_f32_e32 v110, v110
	v_exp_f32_e32 v111, v111
	v_exp_f32_e32 v113, v113
	v_exp_f32_e32 v115, v115
	v_exp_f32_e32 v112, v112
	v_exp_f32_e32 v114, v114
	v_add_f32_e32 v108, 1.0, v108
	v_add_f32_e32 v109, 1.0, v109
	v_add_f32_e32 v110, 1.0, v110
	v_add_f32_e32 v111, 1.0, v111
	v_add_f32_e32 v113, 1.0, v113
	v_add_f32_e32 v115, 1.0, v115
	v_add_f32_e32 v112, 1.0, v112
	v_add_f32_e32 v114, 1.0, v114
	v_rcp_f32_e32 v108, v108
	v_rcp_f32_e32 v109, v109
	v_rcp_f32_e32 v110, v110
	v_rcp_f32_e32 v111, v111
	v_rcp_f32_e32 v113, v113
	v_rcp_f32_e32 v115, v115
	v_rcp_f32_e32 v112, v112
	v_rcp_f32_e32 v114, v114
	v_mul_f32_e32 v107, v107, v108
	v_mul_f32_e32 v93, v93, v109
	v_mul_f32_e32 v101, v101, v110
	v_mul_f32_e32 v95, v95, v111
	v_mul_f32_e32 v89, v89, v113
	v_mul_f32_e32 v91, v91, v115
	v_mul_f32_e32 v103, v103, v112
	v_mul_f32_e32 v97, v97, v114
	v_mul_f32_e32 v106, v106, v107
	v_mul_f32_e32 v92, v92, v93
	v_mul_f32_e32 v93, v100, v101
	v_mul_f32_e32 v94, v94, v95
	v_mul_f32_e32 v100, v88, v89
	v_mul_f32_e32 v91, v90, v91
	v_cvt_pk_bf16_f32 v88, v106, v92
	v_cvt_pk_bf16_f32 v89, v93, v94
	v_mul_f32_e32 v95, v102, v103
	v_mul_f32_e32 v96, v96, v97
	v_cvt_pk_bf16_f32 v90, v95, v100
	v_cvt_pk_bf16_f32 v91, v96, v91
	global_store_dwordx4 v[104:105], v[88:91], off
	s_nop 1
	v_lshl_add_u64 v[88:89], v[98:99], 2, s[8:9]
	s_nop 1
	v_mov_b32_e32 v90, v192
	v_mov_b32_e32 v89, v80
	v_mov_b32_e32 v80, v85
	v_mov_b32_e32 v85, v82
	v_mov_b32_e32 v82, v87
	v_mov_b32_e32 v87, v72
	v_mov_b32_e32 v72, v77
	v_mov_b32_e32 v77, v74
	v_mov_b32_e32 v88, v84
	v_mov_b32_e32 v84, v86
	v_mov_b32_e32 v86, v76
	v_mov_b32_e32 v76, v78
	v_fmamk_f32 v74, v90, 0x3a000000, v167
	v_mul_f32_e32 v78, 0x4f800000, v74
	v_cmp_gt_f32_e32 vcc, s52, v74
	s_nop 1
	v_cndmask_b32_e32 v90, v74, v78, vcc
	v_sqrt_f32_e32 v91, v90
	v_mov_b32_e32 v74, v79
	v_mad_i64_i32 v[78:79], s[0:1], v98, s50, v[154:155]
	v_add_u32_e32 v92, -1, v91
	v_add_u32_e32 v93, 1, v91
	v_fma_f32 v94, -v92, v91, v90
	v_fma_f32 v95, -v93, v91, v90
	v_cmp_ge_f32_e64 s[0:1], 0, v94
	v_lshl_add_u64 v[78:79], v[78:79], 0, v[132:133]
	s_nop 0
	v_cndmask_b32_e64 v91, v91, v92, s[0:1]
	v_cmp_lt_f32_e64 s[0:1], 0, v95
	s_nop 1
	v_cndmask_b32_e64 v91, v91, v93, s[0:1]
	v_mul_f32_e32 v92, 0x37800000, v91
	v_cndmask_b32_e32 v91, v91, v92, vcc
	v_cmp_class_f32_e32 vcc, v90, v168
	s_nop 1
	v_cndmask_b32_e32 v90, v91, v90, vcc
	v_div_scale_f32 v91, s[0:1], v90, v90, 1.0
	v_rcp_f32_e32 v92, v91
	v_div_scale_f32 v93, vcc, 1.0, v90, 1.0
	v_fma_f32 v94, -v91, v92, 1.0
	v_fmac_f32_e32 v92, v94, v92
	v_mul_f32_e32 v94, v93, v92
	v_fma_f32 v95, -v91, v94, v93
	v_fmac_f32_e32 v94, v95, v92
	v_fma_f32 v91, -v91, v94, v93
	v_div_fmas_f32 v91, v91, v92, v94
	v_div_fixup_f32 v90, v91, v90, 1.0
	v_pk_fma_f32 v[74:75], v[74:75], v[90:91], v[66:67] op_sel_hi:[1,0,1]
	v_pk_fma_f32 v[88:89], v[88:89], v[90:91], v[128:129] op_sel_hi:[1,0,1]
	v_pk_fma_f32 v[80:81], v[80:81], v[90:91], v[68:69] op_sel_hi:[1,0,1]
	v_pk_fma_f32 v[84:85], v[84:85], v[90:91], v[130:131] op_sel_hi:[1,0,1]
	v_pk_fma_f32 v[82:83], v[82:83], v[90:91], v[70:71] op_sel_hi:[1,0,1]
	v_pk_fma_f32 v[86:87], v[86:87], v[90:91], v[134:135] op_sel_hi:[1,0,1]
	v_pk_fma_f32 v[72:73], v[72:73], v[90:91], v[64:65] op_sel_hi:[1,0,1]
	v_pk_fma_f32 v[76:77], v[76:77], v[90:91], v[156:157] op_sel_hi:[1,0,1]
	v_mul_f32_e32 v97, 0xbfb8aa3b, v75
	v_mul_f32_e32 v90, 0xbfb8aa3b, v89
	v_mul_f32_e32 v91, 0xbfb8aa3b, v81
	v_mul_f32_e32 v92, 0xbfb8aa3b, v85
	v_mul_f32_e32 v93, 0xbfb8aa3b, v83
	v_mul_f32_e32 v94, 0xbfb8aa3b, v87
	v_mul_f32_e32 v95, 0xbfb8aa3b, v73
	v_mul_f32_e32 v96, 0xbfb8aa3b, v77
	v_exp_f32_e32 v97, v97
	v_exp_f32_e32 v90, v90
	v_exp_f32_e32 v91, v91
	v_exp_f32_e32 v92, v92
	v_exp_f32_e32 v93, v93
	v_exp_f32_e32 v94, v94
	v_exp_f32_e32 v95, v95
	v_exp_f32_e32 v96, v96
	v_add_f32_e32 v97, 1.0, v97
	v_add_f32_e32 v90, 1.0, v90
	v_add_f32_e32 v91, 1.0, v91
	v_add_f32_e32 v92, 1.0, v92
	v_add_f32_e32 v93, 1.0, v93
	v_add_f32_e32 v94, 1.0, v94
	v_add_f32_e32 v95, 1.0, v95
	v_add_f32_e32 v96, 1.0, v96
	v_rcp_f32_e32 v97, v97
	v_rcp_f32_e32 v90, v90
	v_rcp_f32_e32 v91, v91
	v_rcp_f32_e32 v92, v92
	v_rcp_f32_e32 v93, v93
	v_rcp_f32_e32 v94, v94
	v_rcp_f32_e32 v95, v95
	v_rcp_f32_e32 v96, v96
	v_mul_f32_e32 v75, v75, v97
	v_mul_f32_e32 v89, v89, v90
	v_mul_f32_e32 v81, v81, v91
	v_mul_f32_e32 v85, v85, v92
	v_mul_f32_e32 v83, v83, v93
	v_mul_f32_e32 v87, v87, v94
	v_mul_f32_e32 v73, v73, v95
	v_mul_f32_e32 v77, v77, v96
	v_mul_f32_e32 v75, v74, v75
	v_mul_f32_e32 v88, v88, v89
	v_mul_f32_e32 v80, v80, v81
	v_mul_f32_e32 v81, v84, v85
	v_mul_f32_e32 v82, v82, v83
	v_mul_f32_e32 v83, v86, v87
	v_mul_f32_e32 v84, v72, v73
	v_mul_f32_e32 v76, v76, v77
	v_cvt_pk_bf16_f32 v72, v88, v80
	v_cvt_pk_bf16_f32 v73, v81, v82
	v_cvt_pk_bf16_f32 v74, v83, v84
	v_cvt_pk_bf16_f32 v75, v76, v75
	global_store_dwordx4 v[78:79], v[72:75], off
	s_nop 1
	v_mov_b32_e32 v74, v193
	s_nop 0
	v_mov_b32_e32 v72, v60
	v_mov_b32_e32 v60, v62
	v_mov_b32_e32 v62, v52
	v_mov_b32_e32 v52, v54
	v_mov_b32_e32 v73, v56
	v_mov_b32_e32 v56, v61
; __device__ __forceinline__ unsigned cvt_pk_bf16(float lo, float hi) { unsigned r; asm volatile("v_cvt_pk_bf16_f32 %0, %1, %2" : "=v"(r) : "v"(lo), "v"(hi)); return r; }
; __device__ __forceinline__ float siluf(float v) { return v * __builtin_amdgcn_rcpf(1.0f + __expf(-v)); }
;     __device__ __forceinline__ void operator()(const gacc_t (&acc)[2][2][4][2], const Unit& u, int wr, int wc, int fr, int fq) const {
;     ...
;             for (int m = 0; m < 4; ++m) { bf16_t* rowp = O + (size_t)(row0 + ai * 128 + m * 16) * FF + col0;
;                 const float rs = 1.0f / sqrtf(ss[row0 + ai * 128 + m * 16] * (1.0f / D) + NEPS);
;                 const gacc_t a0 = acc[ai][0][m][0], a1 = acc[ai][0][m][1], b0 = acc[ai][1][m][0], b1 = acc[ai][1][m][1];
;                 const float g0[4] = {a0[0] * rs + sg0.x, a0[1] * rs + sg0.y, a0[2] * rs + sg0.z, a0[3] * rs + sg0.w}, g1[4] = {a1[0] * rs + sg1.x, a1[1] * rs + sg1.y, a1[2] * rs + sg1.z, a1[3] * rs + sg1.w};
;                 const float u0[4] = {b0[0] * rs + su0.x, b0[1] * rs + su0.y, b0[2] * rs + su0.z, b0[3] * rs + su0.w}, u1[4] = {b1[0] * rs + su1.x, b1[1] * rs + su1.y, b1[2] * rs + su1.z, b1[3] * rs + su1.w};
;                 u32x4 w;
;                 w.x = pg8::cvt_pk_bf16(siluf(g0[0]) * u0[0], siluf(g0[1]) * u0[1]); w.y = pg8::cvt_pk_bf16(siluf(g0[2]) * u0[2], siluf(g0[3]) * u0[3]);
;                 w.z = pg8::cvt_pk_bf16(siluf(g1[0]) * u1[0], siluf(g1[1]) * u1[1]); w.w = pg8::cvt_pk_bf16(siluf(g1[2]) * u1[2], siluf(g1[3]) * u1[3]);
;                 *(u32x4*)rowp = w; }
	v_mov_b32_e32 v61, v58
	v_mov_b32_e32 v58, v63
	v_mov_b32_e32 v63, v48
	v_mov_b32_e32 v48, v53
	v_mov_b32_e32 v53, v50
	v_mov_b32_e32 v50, v55
	v_fmamk_f32 v54, v74, 0x3a000000, v167
	v_mul_f32_e32 v55, 0x4f800000, v54
	v_cmp_gt_f32_e32 vcc, s52, v54
	s_nop 1
	v_cndmask_b32_e32 v74, v54, v55, vcc
	v_sqrt_f32_e32 v75, v74
	v_add_u32_e32 v54, 0x80, v152
	v_mad_i64_i32 v[54:55], s[0:1], v54, s50, v[154:155]
	v_add_u32_e32 v76, -1, v75
	v_add_u32_e32 v77, 1, v75
	v_fma_f32 v78, -v76, v75, v74
	v_fma_f32 v79, -v77, v75, v74
	v_cmp_ge_f32_e64 s[0:1], 0, v78
	v_lshl_add_u64 v[54:55], v[54:55], 0, v[132:133]
	s_nop 0
	v_cndmask_b32_e64 v75, v75, v76, s[0:1]
	v_cmp_lt_f32_e64 s[0:1], 0, v79
	s_nop 1
	v_cndmask_b32_e64 v75, v75, v77, s[0:1]
	v_mul_f32_e32 v76, 0x37800000, v75
	v_cndmask_b32_e32 v75, v75, v76, vcc
	v_cmp_class_f32_e32 vcc, v74, v168
	s_nop 1
	v_cndmask_b32_e32 v74, v75, v74, vcc
	v_div_scale_f32 v75, s[0:1], v74, v74, 1.0
	v_rcp_f32_e32 v76, v75
	v_div_scale_f32 v77, vcc, 1.0, v74, 1.0
	v_fma_f32 v78, -v75, v76, 1.0
	v_fmac_f32_e32 v76, v78, v76
	v_mul_f32_e32 v78, v77, v76
	v_fma_f32 v79, -v75, v78, v77
	v_fmac_f32_e32 v78, v79, v76
	v_fma_f32 v75, -v75, v78, v77
	v_div_fmas_f32 v75, v75, v76, v78
	v_div_fixup_f32 v74, v75, v74, 1.0
	v_pk_fma_f32 v[50:51], v[50:51], v[74:75], v[66:67] op_sel_hi:[1,0,1]
	v_pk_fma_f32 v[72:73], v[72:73], v[74:75], v[128:129] op_sel_hi:[1,0,1]
	v_pk_fma_f32 v[56:57], v[56:57], v[74:75], v[68:69] op_sel_hi:[1,0,1]
	v_pk_fma_f32 v[60:61], v[60:61], v[74:75], v[130:131] op_sel_hi:[1,0,1]
	v_pk_fma_f32 v[58:59], v[58:59], v[74:75], v[70:71] op_sel_hi:[1,0,1]
	v_pk_fma_f32 v[62:63], v[62:63], v[74:75], v[134:135] op_sel_hi:[1,0,1]
	v_pk_fma_f32 v[48:49], v[48:49], v[74:75], v[64:65] op_sel_hi:[1,0,1]
	v_pk_fma_f32 v[52:53], v[52:53], v[74:75], v[156:157] op_sel_hi:[1,0,1]
	v_mul_f32_e32 v81, 0xbfb8aa3b, v51
	v_mul_f32_e32 v74, 0xbfb8aa3b, v73
	v_mul_f32_e32 v75, 0xbfb8aa3b, v57
	v_mul_f32_e32 v76, 0xbfb8aa3b, v61
	v_mul_f32_e32 v77, 0xbfb8aa3b, v59
	v_mul_f32_e32 v78, 0xbfb8aa3b, v63
	v_mul_f32_e32 v79, 0xbfb8aa3b, v49
	v_mul_f32_e32 v80, 0xbfb8aa3b, v53
	v_exp_f32_e32 v81, v81
	v_exp_f32_e32 v74, v74
	v_exp_f32_e32 v75, v75
	v_exp_f32_e32 v76, v76
	v_exp_f32_e32 v77, v77
	v_exp_f32_e32 v78, v78
	v_exp_f32_e32 v79, v79
	v_exp_f32_e32 v80, v80
	v_add_f32_e32 v81, 1.0, v81
	v_add_f32_e32 v74, 1.0, v74
	v_add_f32_e32 v75, 1.0, v75
	v_add_f32_e32 v76, 1.0, v76
	v_add_f32_e32 v77, 1.0, v77
	v_add_f32_e32 v78, 1.0, v78
	v_add_f32_e32 v79, 1.0, v79
	v_add_f32_e32 v80, 1.0, v80
	v_rcp_f32_e32 v81, v81
	v_rcp_f32_e32 v74, v74
	v_rcp_f32_e32 v75, v75
	v_rcp_f32_e32 v76, v76
	v_rcp_f32_e32 v77, v77
	v_rcp_f32_e32 v78, v78
	v_rcp_f32_e32 v79, v79
	v_rcp_f32_e32 v80, v80
	v_mul_f32_e32 v51, v51, v81
	v_mul_f32_e32 v73, v73, v74
	v_mul_f32_e32 v57, v57, v75
	v_mul_f32_e32 v61, v61, v76
	v_mul_f32_e32 v59, v59, v77
	v_mul_f32_e32 v63, v63, v78
	v_mul_f32_e32 v49, v49, v79
	v_mul_f32_e32 v53, v53, v80
	v_mul_f32_e32 v51, v50, v51
	v_mul_f32_e32 v72, v72, v73
	v_mul_f32_e32 v56, v56, v57
	v_mul_f32_e32 v57, v60, v61
	v_mul_f32_e32 v58, v58, v59
	v_mul_f32_e32 v59, v62, v63
	v_mul_f32_e32 v60, v48, v49
	v_mul_f32_e32 v52, v52, v53
	v_cvt_pk_bf16_f32 v48, v72, v56
	v_cvt_pk_bf16_f32 v49, v57, v58
	v_cvt_pk_bf16_f32 v50, v59, v60
	v_cvt_pk_bf16_f32 v51, v52, v51
	global_store_dwordx4 v[54:55], v[48:51], off
	s_nop 1
	v_mov_b32_e32 v50, v194
	s_nop 0
	v_mov_b32_e32 v48, v44
	v_mov_b32_e32 v44, v46
	v_mov_b32_e32 v46, v36
	v_mov_b32_e32 v36, v38
	v_mov_b32_e32 v49, v40
	v_mov_b32_e32 v40, v45
	v_mov_b32_e32 v45, v42
	v_mov_b32_e32 v42, v47
	v_mov_b32_e32 v47, v32
	v_mov_b32_e32 v32, v37
	v_mov_b32_e32 v37, v34
	v_mov_b32_e32 v34, v39
	v_fmamk_f32 v38, v50, 0x3a000000, v167
	v_mul_f32_e32 v39, 0x4f800000, v38
	v_cmp_gt_f32_e32 vcc, s52, v38
	s_nop 1
	v_cndmask_b32_e32 v50, v38, v39, vcc
	v_sqrt_f32_e32 v51, v50
	v_add_u32_e32 v38, 0x90, v152
	v_mad_i64_i32 v[38:39], s[0:1], v38, s50, v[154:155]
	v_add_u32_e32 v52, -1, v51
	v_add_u32_e32 v53, 1, v51
	v_fma_f32 v54, -v52, v51, v50
	v_fma_f32 v55, -v53, v51, v50
	v_cmp_ge_f32_e64 s[0:1], 0, v54
	v_lshl_add_u64 v[38:39], v[38:39], 0, v[132:133]
	s_nop 0
	v_cndmask_b32_e64 v51, v51, v52, s[0:1]
	v_cmp_lt_f32_e64 s[0:1], 0, v55
	s_nop 1
	v_cndmask_b32_e64 v51, v51, v53, s[0:1]
	v_mul_f32_e32 v52, 0x37800000, v51
	v_cndmask_b32_e32 v51, v51, v52, vcc
	v_cmp_class_f32_e32 vcc, v50, v168
	s_nop 1
	v_cndmask_b32_e32 v50, v51, v50, vcc
	v_div_scale_f32 v51, s[0:1], v50, v50, 1.0
	v_rcp_f32_e32 v52, v51
	v_div_scale_f32 v53, vcc, 1.0, v50, 1.0
	v_fma_f32 v54, -v51, v52, 1.0
	v_fmac_f32_e32 v52, v54, v52
	v_mul_f32_e32 v54, v53, v52
	v_fma_f32 v55, -v51, v54, v53
	v_fmac_f32_e32 v54, v55, v52
	v_fma_f32 v51, -v51, v54, v53
	v_div_fmas_f32 v51, v51, v52, v54
	v_div_fixup_f32 v50, v51, v50, 1.0
	v_pk_fma_f32 v[34:35], v[34:35], v[50:51], v[66:67] op_sel_hi:[1,0,1]
	v_pk_fma_f32 v[48:49], v[48:49], v[50:51], v[128:129] op_sel_hi:[1,0,1]
	v_pk_fma_f32 v[40:41], v[40:41], v[50:51], v[68:69] op_sel_hi:[1,0,1]
	v_pk_fma_f32 v[44:45], v[44:45], v[50:51], v[130:131] op_sel_hi:[1,0,1]
	v_pk_fma_f32 v[42:43], v[42:43], v[50:51], v[70:71] op_sel_hi:[1,0,1]
	v_pk_fma_f32 v[46:47], v[46:47], v[50:51], v[134:135] op_sel_hi:[1,0,1]
	v_pk_fma_f32 v[32:33], v[32:33], v[50:51], v[64:65] op_sel_hi:[1,0,1]
	v_pk_fma_f32 v[36:37], v[36:37], v[50:51], v[156:157] op_sel_hi:[1,0,1]
	v_mul_f32_e32 v57, 0xbfb8aa3b, v35
	v_mul_f32_e32 v50, 0xbfb8aa3b, v49
	v_mul_f32_e32 v51, 0xbfb8aa3b, v41
	v_mul_f32_e32 v52, 0xbfb8aa3b, v45
	v_mul_f32_e32 v53, 0xbfb8aa3b, v43
	v_mul_f32_e32 v54, 0xbfb8aa3b, v47
; __device__ __forceinline__ unsigned cvt_pk_bf16(float lo, float hi) { unsigned r; asm volatile("v_cvt_pk_bf16_f32 %0, %1, %2" : "=v"(r) : "v"(lo), "v"(hi)); return r; }
; __device__ __forceinline__ float siluf(float v) { return v * __builtin_amdgcn_rcpf(1.0f + __expf(-v)); }
;     __device__ __forceinline__ void operator()(const gacc_t (&acc)[2][2][4][2], const Unit& u, int wr, int wc, int fr, int fq) const {
;     ...
;             for (int m = 0; m < 4; ++m) { bf16_t* rowp = O + (size_t)(row0 + ai * 128 + m * 16) * FF + col0;
;                 const float rs = 1.0f / sqrtf(ss[row0 + ai * 128 + m * 16] * (1.0f / D) + NEPS);
;                 const gacc_t a0 = acc[ai][0][m][0], a1 = acc[ai][0][m][1], b0 = acc[ai][1][m][0], b1 = acc[ai][1][m][1];
;                 const float g0[4] = {a0[0] * rs + sg0.x, a0[1] * rs + sg0.y, a0[2] * rs + sg0.z, a0[3] * rs + sg0.w}, g1[4] = {a1[0] * rs + sg1.x, a1[1] * rs + sg1.y, a1[2] * rs + sg1.z, a1[3] * rs + sg1.w};
;                 const float u0[4] = {b0[0] * rs + su0.x, b0[1] * rs + su0.y, b0[2] * rs + su0.z, b0[3] * rs + su0.w}, u1[4] = {b1[0] * rs + su1.x, b1[1] * rs + su1.y, b1[2] * rs + su1.z, b1[3] * rs + su1.w};
;                 u32x4 w;
;                 w.x = pg8::cvt_pk_bf16(siluf(g0[0]) * u0[0], siluf(g0[1]) * u0[1]); w.y = pg8::cvt_pk_bf16(siluf(g0[2]) * u0[2], siluf(g0[3]) * u0[3]);
;                 w.z = pg8::cvt_pk_bf16(siluf(g1[0]) * u1[0], siluf(g1[1]) * u1[1]); w.w = pg8::cvt_pk_bf16(siluf(g1[2]) * u1[2], siluf(g1[3]) * u1[3]);
;                 *(u32x4*)rowp = w; }
	v_mul_f32_e32 v55, 0xbfb8aa3b, v33
	v_mul_f32_e32 v56, 0xbfb8aa3b, v37
	v_exp_f32_e32 v57, v57
	v_exp_f32_e32 v50, v50
	v_exp_f32_e32 v51, v51
	v_exp_f32_e32 v52, v52
	v_exp_f32_e32 v53, v53
	v_exp_f32_e32 v54, v54
	v_exp_f32_e32 v55, v55
	v_exp_f32_e32 v56, v56
	v_add_f32_e32 v57, 1.0, v57
	v_add_f32_e32 v50, 1.0, v50
	v_add_f32_e32 v51, 1.0, v51
	v_add_f32_e32 v52, 1.0, v52
	v_add_f32_e32 v53, 1.0, v53
	v_add_f32_e32 v54, 1.0, v54
	v_add_f32_e32 v55, 1.0, v55
	v_add_f32_e32 v56, 1.0, v56
	v_rcp_f32_e32 v57, v57
	v_rcp_f32_e32 v50, v50
	v_rcp_f32_e32 v51, v51
	v_rcp_f32_e32 v52, v52
	v_rcp_f32_e32 v53, v53
	v_rcp_f32_e32 v54, v54
	v_rcp_f32_e32 v55, v55
	v_rcp_f32_e32 v56, v56
	v_mul_f32_e32 v35, v35, v57
	v_mul_f32_e32 v49, v49, v50
	v_mul_f32_e32 v41, v41, v51
	v_mul_f32_e32 v45, v45, v52
	v_mul_f32_e32 v43, v43, v53
	v_mul_f32_e32 v47, v47, v54
	v_mul_f32_e32 v33, v33, v55
	v_mul_f32_e32 v37, v37, v56
	v_mul_f32_e32 v35, v34, v35
	v_mul_f32_e32 v48, v48, v49
	v_mul_f32_e32 v40, v40, v41
	v_mul_f32_e32 v41, v44, v45
	v_mul_f32_e32 v42, v42, v43
	v_mul_f32_e32 v43, v46, v47
	v_mul_f32_e32 v44, v32, v33
	v_mul_f32_e32 v36, v36, v37
	v_cvt_pk_bf16_f32 v32, v48, v40
	v_cvt_pk_bf16_f32 v33, v41, v42
	v_cvt_pk_bf16_f32 v34, v43, v44
	v_cvt_pk_bf16_f32 v35, v36, v35
	global_store_dwordx4 v[38:39], v[32:35], off
	s_nop 1
	v_mov_b32_e32 v34, v195
	s_nop 0
	v_mov_b32_e32 v32, v28
	v_mov_b32_e32 v28, v30
	v_mov_b32_e32 v30, v20
	v_mov_b32_e32 v20, v22
	v_mov_b32_e32 v33, v24
	v_mov_b32_e32 v24, v29
	v_mov_b32_e32 v29, v26
	v_mov_b32_e32 v26, v31
	v_mov_b32_e32 v31, v16
	v_mov_b32_e32 v16, v21
	v_mov_b32_e32 v21, v18
	v_mov_b32_e32 v18, v23
	v_fmamk_f32 v22, v34, 0x3a000000, v167
	v_mul_f32_e32 v23, 0x4f800000, v22
	v_cmp_gt_f32_e32 vcc, s52, v22
	s_nop 1
	v_cndmask_b32_e32 v34, v22, v23, vcc
	v_sqrt_f32_e32 v35, v34
	v_add_u32_e32 v22, 0xa0, v152
	v_mad_i64_i32 v[22:23], s[0:1], v22, s50, v[154:155]
	v_add_u32_e32 v36, -1, v35
	v_add_u32_e32 v37, 1, v35
	v_fma_f32 v38, -v36, v35, v34
	v_fma_f32 v39, -v37, v35, v34
	v_cmp_ge_f32_e64 s[0:1], 0, v38
	v_lshl_add_u64 v[22:23], v[22:23], 0, v[132:133]
	s_nop 0
	v_cndmask_b32_e64 v35, v35, v36, s[0:1]
	v_cmp_lt_f32_e64 s[0:1], 0, v39
	s_nop 1
	v_cndmask_b32_e64 v35, v35, v37, s[0:1]
	v_mul_f32_e32 v36, 0x37800000, v35
	v_cndmask_b32_e32 v35, v35, v36, vcc
	v_cmp_class_f32_e32 vcc, v34, v168
	s_nop 1
	v_cndmask_b32_e32 v34, v35, v34, vcc
	v_div_scale_f32 v35, s[0:1], v34, v34, 1.0
	v_rcp_f32_e32 v36, v35
	v_div_scale_f32 v37, vcc, 1.0, v34, 1.0
	v_fma_f32 v38, -v35, v36, 1.0
	v_fmac_f32_e32 v36, v38, v36
	v_mul_f32_e32 v38, v37, v36
	v_fma_f32 v39, -v35, v38, v37
	v_fmac_f32_e32 v38, v39, v36
	v_fma_f32 v35, -v35, v38, v37
	v_div_fmas_f32 v35, v35, v36, v38
	v_div_fixup_f32 v34, v35, v34, 1.0
	v_pk_fma_f32 v[18:19], v[18:19], v[34:35], v[66:67] op_sel_hi:[1,0,1]
	v_pk_fma_f32 v[32:33], v[32:33], v[34:35], v[128:129] op_sel_hi:[1,0,1]
	v_pk_fma_f32 v[24:25], v[24:25], v[34:35], v[68:69] op_sel_hi:[1,0,1]
	v_pk_fma_f32 v[28:29], v[28:29], v[34:35], v[130:131] op_sel_hi:[1,0,1]
	v_pk_fma_f32 v[26:27], v[26:27], v[34:35], v[70:71] op_sel_hi:[1,0,1]
	v_pk_fma_f32 v[30:31], v[30:31], v[34:35], v[134:135] op_sel_hi:[1,0,1]
	v_pk_fma_f32 v[16:17], v[16:17], v[34:35], v[64:65] op_sel_hi:[1,0,1]
	v_pk_fma_f32 v[20:21], v[20:21], v[34:35], v[156:157] op_sel_hi:[1,0,1]
	v_mul_f32_e32 v41, 0xbfb8aa3b, v19
	v_mul_f32_e32 v34, 0xbfb8aa3b, v33
	v_mul_f32_e32 v35, 0xbfb8aa3b, v25
	v_mul_f32_e32 v36, 0xbfb8aa3b, v29
	v_mul_f32_e32 v37, 0xbfb8aa3b, v27
	v_mul_f32_e32 v38, 0xbfb8aa3b, v31
	v_mul_f32_e32 v39, 0xbfb8aa3b, v17
	v_mul_f32_e32 v40, 0xbfb8aa3b, v21
	v_exp_f32_e32 v41, v41
	v_exp_f32_e32 v34, v34
	v_exp_f32_e32 v35, v35
	v_exp_f32_e32 v36, v36
	v_exp_f32_e32 v37, v37
	v_exp_f32_e32 v38, v38
	v_exp_f32_e32 v39, v39
	v_exp_f32_e32 v40, v40
	v_add_f32_e32 v41, 1.0, v41
	v_add_f32_e32 v34, 1.0, v34
	v_add_f32_e32 v35, 1.0, v35
	v_add_f32_e32 v36, 1.0, v36
	v_add_f32_e32 v37, 1.0, v37
	v_add_f32_e32 v38, 1.0, v38
	v_add_f32_e32 v39, 1.0, v39
	v_add_f32_e32 v40, 1.0, v40
	v_rcp_f32_e32 v41, v41
	v_rcp_f32_e32 v34, v34
	v_rcp_f32_e32 v35, v35
	v_rcp_f32_e32 v36, v36
	v_rcp_f32_e32 v37, v37
	v_rcp_f32_e32 v38, v38
	v_rcp_f32_e32 v39, v39
	v_rcp_f32_e32 v40, v40
	v_mul_f32_e32 v19, v19, v41
; __device__ __forceinline__ unsigned cvt_pk_bf16(float lo, float hi) { unsigned r; asm volatile("v_cvt_pk_bf16_f32 %0, %1, %2" : "=v"(r) : "v"(lo), "v"(hi)); return r; }
; __device__ __forceinline__ float siluf(float v) { return v * __builtin_amdgcn_rcpf(1.0f + __expf(-v)); }
;     __device__ __forceinline__ void operator()(const gacc_t (&acc)[2][2][4][2], const Unit& u, int wr, int wc, int fr, int fq) const {
;     ...
;             for (int m = 0; m < 4; ++m) { bf16_t* rowp = O + (size_t)(row0 + ai * 128 + m * 16) * FF + col0;
;                 const float rs = 1.0f / sqrtf(ss[row0 + ai * 128 + m * 16] * (1.0f / D) + NEPS);
;                 const gacc_t a0 = acc[ai][0][m][0], a1 = acc[ai][0][m][1], b0 = acc[ai][1][m][0], b1 = acc[ai][1][m][1];
;                 const float g0[4] = {a0[0] * rs + sg0.x, a0[1] * rs + sg0.y, a0[2] * rs + sg0.z, a0[3] * rs + sg0.w}, g1[4] = {a1[0] * rs + sg1.x, a1[1] * rs + sg1.y, a1[2] * rs + sg1.z, a1[3] * rs + sg1.w};
;                 const float u0[4] = {b0[0] * rs + su0.x, b0[1] * rs + su0.y, b0[2] * rs + su0.z, b0[3] * rs + su0.w}, u1[4] = {b1[0] * rs + su1.x, b1[1] * rs + su1.y, b1[2] * rs + su1.z, b1[3] * rs + su1.w};
;                 u32x4 w;
;                 w.x = pg8::cvt_pk_bf16(siluf(g0[0]) * u0[0], siluf(g0[1]) * u0[1]); w.y = pg8::cvt_pk_bf16(siluf(g0[2]) * u0[2], siluf(g0[3]) * u0[3]);
;                 w.z = pg8::cvt_pk_bf16(siluf(g1[0]) * u1[0], siluf(g1[1]) * u1[1]); w.w = pg8::cvt_pk_bf16(siluf(g1[2]) * u1[2], siluf(g1[3]) * u1[3]);
;                 *(u32x4*)rowp = w; }
	v_mul_f32_e32 v33, v33, v34
	v_mul_f32_e32 v25, v25, v35
	v_mul_f32_e32 v29, v29, v36
	v_mul_f32_e32 v27, v27, v37
	v_mul_f32_e32 v31, v31, v38
	v_mul_f32_e32 v17, v17, v39
	v_mul_f32_e32 v21, v21, v40
	v_mul_f32_e32 v19, v18, v19
	v_mul_f32_e32 v32, v32, v33
	v_mul_f32_e32 v24, v24, v25
	v_mul_f32_e32 v25, v28, v29
	v_mul_f32_e32 v26, v26, v27
	v_mul_f32_e32 v27, v30, v31
	v_mul_f32_e32 v28, v16, v17
	v_mul_f32_e32 v20, v20, v21
	v_cvt_pk_bf16_f32 v16, v32, v24
	v_cvt_pk_bf16_f32 v17, v25, v26
	v_cvt_pk_bf16_f32 v18, v27, v28
	v_cvt_pk_bf16_f32 v19, v20, v19
	global_store_dwordx4 v[22:23], v[16:19], off
	s_nop 1
	v_mov_b32_e32 v18, v196
	s_nop 0
	v_mov_b32_e32 v17, v4
	v_mov_b32_e32 v4, v13
	v_mov_b32_e32 v13, v6
	v_mov_b32_e32 v6, v15
	v_mov_b32_e32 v15, v0
	v_mov_b32_e32 v0, v9
	v_mov_b32_e32 v9, v2
	v_mov_b32_e32 v2, v11
	v_mov_b32_e32 v16, v12
	v_mov_b32_e32 v12, v14
	v_mov_b32_e32 v14, v8
	v_mov_b32_e32 v8, v10
	v_add_u32_e32 v10, 0xb0, v152
	v_fmamk_f32 v11, v18, 0x3a000000, v167
	v_mul_f32_e32 v18, 0x4f800000, v11
	v_cmp_gt_f32_e32 vcc, s52, v11
	s_nop 1
	v_cndmask_b32_e32 v18, v11, v18, vcc
	v_sqrt_f32_e32 v19, v18
	v_mad_i64_i32 v[10:11], s[0:1], v10, s50, v[154:155]
	v_lshl_add_u64 v[10:11], v[10:11], 0, v[132:133]
	v_add_u32_e32 v20, -1, v19
	v_add_u32_e32 v21, 1, v19
	v_fma_f32 v22, -v20, v19, v18
	v_fma_f32 v23, -v21, v19, v18
	v_cmp_ge_f32_e64 s[0:1], 0, v22
	s_nop 1
	v_cndmask_b32_e64 v19, v19, v20, s[0:1]
	v_cmp_lt_f32_e64 s[0:1], 0, v23
	s_nop 1
	v_cndmask_b32_e64 v19, v19, v21, s[0:1]
	v_mul_f32_e32 v20, 0x37800000, v19
	v_cndmask_b32_e32 v19, v19, v20, vcc
	v_cmp_class_f32_e32 vcc, v18, v168
	s_nop 1
	v_cndmask_b32_e32 v18, v19, v18, vcc
	v_div_scale_f32 v19, s[0:1], v18, v18, 1.0
	v_rcp_f32_e32 v20, v19
	v_div_scale_f32 v21, vcc, 1.0, v18, 1.0
	s_mov_b64 s[0:1], -1
	v_fma_f32 v22, -v19, v20, 1.0
	v_fmac_f32_e32 v20, v22, v20
	v_mul_f32_e32 v22, v21, v20
	v_fma_f32 v23, -v19, v22, v21
	v_fmac_f32_e32 v22, v23, v20
	v_fma_f32 v19, -v19, v22, v21
	v_div_fmas_f32 v19, v19, v20, v22
	v_div_fixup_f32 v18, v19, v18, 1.0
	v_pk_fma_f32 v[2:3], v[2:3], v[18:19], v[66:67] op_sel_hi:[1,0,1]
	v_pk_fma_f32 v[16:17], v[16:17], v[18:19], v[128:129] op_sel_hi:[1,0,1]
	v_pk_fma_f32 v[4:5], v[4:5], v[18:19], v[68:69] op_sel_hi:[1,0,1]
	v_pk_fma_f32 v[12:13], v[12:13], v[18:19], v[130:131] op_sel_hi:[1,0,1]
	v_pk_fma_f32 v[6:7], v[6:7], v[18:19], v[70:71] op_sel_hi:[1,0,1]
	v_pk_fma_f32 v[14:15], v[14:15], v[18:19], v[134:135] op_sel_hi:[1,0,1]
	v_pk_fma_f32 v[0:1], v[0:1], v[18:19], v[64:65] op_sel_hi:[1,0,1]
	v_pk_fma_f32 v[8:9], v[8:9], v[18:19], v[156:157] op_sel_hi:[1,0,1]
	v_mul_f32_e32 v25, 0xbfb8aa3b, v3
	v_mul_f32_e32 v18, 0xbfb8aa3b, v17
	v_mul_f32_e32 v19, 0xbfb8aa3b, v5
	v_mul_f32_e32 v20, 0xbfb8aa3b, v13
	v_mul_f32_e32 v21, 0xbfb8aa3b, v7
	v_mul_f32_e32 v22, 0xbfb8aa3b, v15
	v_mul_f32_e32 v23, 0xbfb8aa3b, v1
	v_mul_f32_e32 v24, 0xbfb8aa3b, v9
	v_exp_f32_e32 v25, v25
	v_exp_f32_e32 v18, v18
	v_exp_f32_e32 v19, v19
	v_exp_f32_e32 v20, v20
	v_exp_f32_e32 v21, v21
	v_exp_f32_e32 v22, v22
	v_exp_f32_e32 v23, v23
	v_exp_f32_e32 v24, v24
	v_add_f32_e32 v25, 1.0, v25
	v_add_f32_e32 v18, 1.0, v18
	v_add_f32_e32 v19, 1.0, v19
	v_add_f32_e32 v20, 1.0, v20
	v_add_f32_e32 v21, 1.0, v21
	v_add_f32_e32 v22, 1.0, v22
	v_add_f32_e32 v23, 1.0, v23
	v_add_f32_e32 v24, 1.0, v24
	v_rcp_f32_e32 v25, v25
	v_rcp_f32_e32 v18, v18
	v_rcp_f32_e32 v19, v19
	v_rcp_f32_e32 v20, v20
	v_rcp_f32_e32 v21, v21
	v_rcp_f32_e32 v22, v22
	v_rcp_f32_e32 v23, v23
	v_rcp_f32_e32 v24, v24
	v_mul_f32_e32 v3, v3, v25
	s_andn2_b64 vcc, exec, s[2:3]
	v_mul_f32_e32 v17, v17, v18
	v_mul_f32_e32 v5, v5, v19
	v_mul_f32_e32 v13, v13, v20
	v_mul_f32_e32 v7, v7, v21
	v_mul_f32_e32 v15, v15, v22
	v_mul_f32_e32 v1, v1, v23
	v_mul_f32_e32 v9, v9, v24
	v_mul_f32_e32 v3, v2, v3
	v_mul_f32_e32 v16, v16, v17
	v_mul_f32_e32 v4, v4, v5
	v_mul_f32_e32 v5, v12, v13
	v_mul_f32_e32 v6, v6, v7
	v_mul_f32_e32 v7, v14, v15
	v_mul_f32_e32 v12, v0, v1
	v_mul_f32_e32 v8, v8, v9
	v_cvt_pk_bf16_f32 v0, v16, v4
	v_cvt_pk_bf16_f32 v1, v5, v6
	v_cvt_pk_bf16_f32 v2, v7, v12
	v_cvt_pk_bf16_f32 v3, v8, v3
	global_store_dwordx4 v[10:11], v[0:3], off
	s_cbranch_vccnz .LBB0_1594
	s_andn2_b64 vcc, exec, s[4:5]
	s_cbranch_vccnz .LBB0_1593
	s_barrier
	s_branch .LBB0_1593
